# MFMA order: second 16-group of each block walks the snake in reverse so the group boundary also shares a source operand
# speedup vs baseline: 1.0269x; 1.0016x over previous
; #define PG8_LAS __attribute__((address_space(3)))
; #define PG8_STAGE(bufoff, gbase, voff) do { _Pragma("unroll") for (int _i = 0; _i < 2; ++_i) \
;         __builtin_amdgcn_global_load_lds((const unsigned*)((const char*)(gbase) + (voff)[_i]), (PG8_LAS unsigned*)(lds + (bufoff) + ldsw + _i * 8192), 16, 0, 0); } while (0)
; #define PG8_LDA(dst, b, h) do { _Pragma("unroll") for (int m = 0; m < 4; ++m) _Pragma("unroll") for (int k = 0; k < 2; ++k) dst[m][k] = *(const PG8_LAS bf16x8*)(lds + PG8_SA(b, h) + aoff + m * 2048 + k * 1024); } while (0)
; template <class Epi, class Sched, bool ALIGN_EPI = false, bool SP2 = false, bool RS = false, bool BPRE = false>
; __device__ __forceinline__ void gemm_phase(PG8_LAS unsigned char* lds, const Gemm g, const Sched& S, const Epi& E, const float* rs_ss = nullptr, PG8_LAS float* rs_tab = nullptr) {
;     ...
;         const bool has_next = S.next(ui + 1, nxt);
;         const char* nA = has_next ? (const char*)g.A + (size_t)nxt.pm * tstep : cA; const char* nB = has_next ? (const char*)g.Bt + (size_t)nxt.pn * tstep : cB;
;         for (int t = 0; t < nt; t += 2) {
;             const bool last = (t == nt - 2);
;             if constexpr (RS) { if (t == 16 || t == 32) { const PG8_LAS float* tp = rs_tab + (ui & 1) * 768 + (t == 32 ? 256 : 0);
;                 _Pragma("unroll") for (int a = 0; a < 2; ++a) _Pragma("unroll") for (int m = 0; m < 4; ++m) { const float f = tp[a * HALF + wr * 64 + m * 16 + fr];
;                     _Pragma("unroll") for (int b = 0; b < 2; ++b) _Pragma("unroll") for (int n = 0; n < 2; ++n) acc[a][b][m][n] = acc[a][b][m][n] * f; } } }
;             const char* a1 = cA + (size_t)(t + 1) * kstep;
;             const char* a2 = last ? nA : cA + (size_t)(t + 2) * kstep; const char* b2 = last ? nB : cB + (size_t)(t + 2) * kstep;
;             const char* a3 = a2 + kstep; const char* b3 = b2 + kstep;
;             if (last && has_next) S.a_ready(nxt);
;             if constexpr (SP2) {
;             PG8_LDB(B0, 0, 0); PG8_LDB(B1, 0, 1); PG8_SCHED; PG8_LDA(At, 0, 0); PG8_STAGE(PG8_SA(1, 1), a1 + hstep, voffA);
;             PG8_WAIT_V(8); PG8_WAIT_L(0); PG8_BAR; PG8_MMA(0, 0, At, B0); PG8_MMA(0, 1, At, B1); PG8_BAR; PG8_SCHED;
;             PG8_LDA(At, 0, 1); PG8_STAGE(PG8_SB(0, 0), b2, voffB); PG8_STAGE(PG8_SB(0, 1), b2 + hstep, voffB); PG8_STAGE(PG8_SA(0, 0), a2, voffA);
.LBB0_195:
	s_ashr_i32 s19, s18, 31
	s_lshl_b64 s[20:21], s[18:19], 20
	s_add_u32 s20, s30, s20
	s_addc_u32 s21, s31, s21
	s_and_b64 s[44:45], s[6:7], exec
	s_cselect_b32 s5, s21, s57
	s_cselect_b32 s19, s20, s56
	s_ashr_i32 s17, s16, 31
	s_lshl_b64 s[44:45], s[16:17], 20
	s_add_u32 s44, s24, s44
	s_addc_u32 s45, s25, s45
	s_and_b64 s[60:61], s[6:7], exec
	s_cselect_b32 s17, s45, s59
	s_cselect_b32 s47, s44, s58
	s_add_u32 s56, s56, 0x84000
	s_addc_u32 s57, s57, 0
	s_add_u32 s87, s58, 0x8000
	s_addc_u32 s88, s59, 0
	s_mov_b32 s89, -2
	s_waitcnt lgkmcnt(0)
	ds_read_b128 v[130:133], v161
	ds_read_b128 v[134:137], v161 offset:1024
	ds_read_b128 v[152:155], v161 offset:2048
	ds_read_b128 v[156:159], v161 offset:3072
	ds_read_b128 v[166:169], v162
	ds_read_b128 v[170:173], v162 offset:1024
	ds_read_b128 v[174:177], v162 offset:2048
	ds_read_b128 v[182:185], v162 offset:3072
	s_add_u32 s58, s56, 0xfff84000
	s_addc_u32 s59, s57, -1
	s_cmp_eq_u32 s89, 28
	s_cselect_b32 s70, s19, s58
	s_cselect_b32 s71, s5, s59
	s_cselect_b32 s60, s47, s87
	s_cselect_b32 s61, s17, s88
	s_add_u32 s58, s70, 0x4000
	s_addc_u32 s59, s71, 0
	v_lshl_add_u64 v[178:179], s[56:57], 0, v[138:139]
	s_add_i32 m0, s72, 0xc000
	ds_read_b128 v[186:189], v163
	ds_read_b128 v[190:193], v163 offset:1024
	ds_read_b128 v[194:197], v163 offset:2048
	ds_read_b128 v[198:201], v163 offset:3072
	ds_read_b128 v[202:205], v163 offset:4096
	ds_read_b128 v[206:209], v163 offset:5120
	ds_read_b128 v[210:213], v163 offset:6144
	ds_read_b128 v[214:217], v163 offset:7168
	global_load_lds_dwordx4 v[178:179], off
	v_lshl_add_u64 v[178:179], s[56:57], 0, v[146:147]
	s_add_i32 m0, s72, 0xe000
	s_nop 0
	global_load_lds_dwordx4 v[178:179], off
	s_waitcnt vmcnt(8)
	s_waitcnt lgkmcnt(0)
	s_barrier
	s_setprio 1
	s_waitcnt lgkmcnt(0)
	v_mfma_f32_16x16x32_bf16 v[126:129], v[130:133], v[186:189], 0
	v_mfma_f32_16x16x32_bf16 v[126:129], v[134:137], v[190:193], v[126:129]
	v_mfma_f32_16x16x32_bf16 v[122:125], v[156:159], v[190:193], 0
	v_mfma_f32_16x16x32_bf16 v[122:125], v[152:155], v[186:189], v[122:125]
	v_mfma_f32_16x16x32_bf16 v[106:109], v[152:155], v[194:197], 0
	v_mfma_f32_16x16x32_bf16 v[106:109], v[156:159], v[198:201], v[106:109]
	v_mfma_f32_16x16x32_bf16 v[110:113], v[134:137], v[198:201], 0
	v_mfma_f32_16x16x32_bf16 v[110:113], v[130:133], v[194:197], v[110:113]
	v_mfma_f32_16x16x32_bf16 v[94:97], v[130:133], v[202:205], 0
	v_mfma_f32_16x16x32_bf16 v[94:97], v[134:137], v[206:209], v[94:97]
	v_mfma_f32_16x16x32_bf16 v[90:93], v[156:159], v[206:209], 0
	v_mfma_f32_16x16x32_bf16 v[90:93], v[152:155], v[202:205], v[90:93]
	v_mfma_f32_16x16x32_bf16 v[74:77], v[152:155], v[210:213], 0
	v_mfma_f32_16x16x32_bf16 v[74:77], v[156:159], v[214:217], v[74:77]
	v_mfma_f32_16x16x32_bf16 v[78:81], v[134:137], v[214:217], 0
	v_mfma_f32_16x16x32_bf16 v[78:81], v[130:133], v[210:213], v[78:81]
	s_setprio 0
	s_setprio 1
	v_mfma_f32_16x16x32_bf16 v[70:73], v[166:169], v[210:213], 0
	v_mfma_f32_16x16x32_bf16 v[70:73], v[170:173], v[214:217], v[70:73]
	v_mfma_f32_16x16x32_bf16 v[66:69], v[182:185], v[214:217], 0
	v_mfma_f32_16x16x32_bf16 v[66:69], v[174:177], v[210:213], v[66:69]
	v_mfma_f32_16x16x32_bf16 v[82:85], v[174:177], v[202:205], 0
	v_mfma_f32_16x16x32_bf16 v[82:85], v[182:185], v[206:209], v[82:85]
	v_mfma_f32_16x16x32_bf16 v[86:89], v[170:173], v[206:209], 0
	v_mfma_f32_16x16x32_bf16 v[86:89], v[166:169], v[202:205], v[86:89]
	v_mfma_f32_16x16x32_bf16 v[102:105], v[166:169], v[194:197], 0
	v_mfma_f32_16x16x32_bf16 v[102:105], v[170:173], v[198:201], v[102:105]
	v_mfma_f32_16x16x32_bf16 v[98:101], v[182:185], v[198:201], 0
	v_mfma_f32_16x16x32_bf16 v[98:101], v[174:177], v[194:197], v[98:101]
	v_mfma_f32_16x16x32_bf16 v[114:117], v[174:177], v[186:189], 0
	v_mfma_f32_16x16x32_bf16 v[114:117], v[182:185], v[190:193], v[114:117]
	v_mfma_f32_16x16x32_bf16 v[118:121], v[170:173], v[190:193], 0
	v_mfma_f32_16x16x32_bf16 v[118:121], v[166:169], v[186:189], v[118:121]
	s_setprio 0
	s_barrier
	s_add_i32 s90, s83, s15
	v_lshl_add_u64 v[178:179], s[60:61], 0, v[138:139]
	s_mov_b32 m0, s90
	ds_read_b128 v[186:189], v163 offset:16384
	ds_read_b128 v[190:193], v163 offset:17408
	ds_read_b128 v[194:197], v163 offset:18432
	ds_read_b128 v[198:201], v163 offset:19456
	ds_read_b128 v[202:205], v163 offset:20480
	ds_read_b128 v[206:209], v163 offset:21504
	ds_read_b128 v[210:213], v163 offset:22528
	ds_read_b128 v[214:217], v163 offset:23552
	global_load_lds_dwordx4 v[178:179], off
	s_add_i32 m0, s90, 0x2000
	s_add_u32 s90, s60, 0x80000
	v_lshl_add_u64 v[178:179], s[60:61], 0, v[140:141]
	s_addc_u32 s91, s61, 0
	s_add_i32 s92, s86, s15
	global_load_lds_dwordx4 v[178:179], off
	v_lshl_add_u64 v[178:179], s[90:91], 0, v[138:139]
	s_mov_b32 m0, s92
	s_nop 0
	global_load_lds_dwordx4 v[178:179], off
	v_lshl_add_u64 v[178:179], s[90:91], 0, v[140:141]
	s_add_i32 m0, s92, 0x2000
	s_nop 0
	global_load_lds_dwordx4 v[178:179], off
	v_lshl_add_u64 v[178:179], s[70:71], 0, v[138:139]
	s_mov_b32 m0, s72
	s_nop 0
	global_load_lds_dwordx4 v[178:179], off
	v_lshl_add_u64 v[178:179], s[70:71], 0, v[140:141]
	s_mov_b32 m0, s73
	s_nop 0
	global_load_lds_dwordx4 v[178:179], off
	s_waitcnt vmcnt(8)
	s_waitcnt lgkmcnt(0)
	s_barrier
; #define PG8_STAGE(bufoff, gbase, voff) do { _Pragma("unroll") for (int _i = 0; _i < 2; ++_i) \
;         __builtin_amdgcn_global_load_lds((const unsigned*)((const char*)(gbase) + (voff)[_i]), (PG8_LAS unsigned*)(lds + (bufoff) + ldsw + _i * 8192), 16, 0, 0); } while (0)
; #define PG8_LDA(dst, b, h) do { _Pragma("unroll") for (int m = 0; m < 4; ++m) _Pragma("unroll") for (int k = 0; k < 2; ++k) dst[m][k] = *(const PG8_LAS bf16x8*)(lds + PG8_SA(b, h) + aoff + m * 2048 + k * 1024); } while (0)
; #define PG8_LDB(dst, b, h) do { _Pragma("unroll") for (int n = 0; n < 2; ++n) _Pragma("unroll") for (int k = 0; k < 2; ++k) dst[n][k] = *(const PG8_LAS bf16x8*)(lds + PG8_SB(b, h) + boff + n * 2048 + k * 1024); } while (0)
; #define PG8_MMA(ai, bj, At, Bt) do { __builtin_amdgcn_s_setprio(1); _Pragma("unroll") for (int m = 0; m < 4; ++m) _Pragma("unroll") for (int n = 0; n < 2; ++n) _Pragma("unroll") for (int k = 0; k < 2; ++k) \
;         acc[ai][bj][m][n] = __builtin_amdgcn_mfma_f32_16x16x32_bf16(Bt[n][k], At[m][k], acc[ai][bj][m][n], 0, 0, 0); __builtin_amdgcn_s_setprio(0); } while (0)
; #define PG8_WAIT_V(n) asm volatile("s_waitcnt vmcnt(" #n ")" ::: "memory")
; #define PG8_WAIT_L(n) asm volatile("s_waitcnt lgkmcnt(" #n ")" ::: "memory")
; #define PG8_BAR __builtin_amdgcn_s_barrier()
; #define PG8_SCHED __builtin_amdgcn_sched_barrier(0)
; template <class Epi, class Sched, bool ALIGN_EPI = false, bool SP2 = false, bool RS = false, bool BPRE = false>
; __device__ __forceinline__ void gemm_phase(PG8_LAS unsigned char* lds, const Gemm g, const Sched& S, const Epi& E, const float* rs_ss = nullptr, PG8_LAS float* rs_tab = nullptr) {
;     ...
;             PG8_LDA(At, 0, 1); PG8_STAGE(PG8_SB(0, 0), b2, voffB); PG8_STAGE(PG8_SB(0, 1), b2 + hstep, voffB); PG8_STAGE(PG8_SA(0, 0), a2, voffA);
;             PG8_WAIT_V(8); PG8_WAIT_L(0); PG8_BAR; PG8_MMA(1, 0, At, B0); PG8_MMA(1, 1, At, B1); PG8_BAR; PG8_SCHED;
;             PG8_LDB(B0, 1, 0); PG8_LDB(B1, 1, 1); PG8_SCHED; PG8_LDA(At, 1, 0); PG8_STAGE(PG8_SA(0, 1), a2 + hstep, voffA);
;             PG8_WAIT_V(8); PG8_WAIT_L(0); PG8_BAR; PG8_MMA(0, 0, At, B0); PG8_MMA(0, 1, At, B1); PG8_BAR; PG8_SCHED;
	s_setprio 1
	s_waitcnt lgkmcnt(0)
	v_mfma_f32_16x16x32_bf16 v[62:65], v[130:133], v[186:189], 0
	v_mfma_f32_16x16x32_bf16 v[62:65], v[134:137], v[190:193], v[62:65]
	v_mfma_f32_16x16x32_bf16 v[58:61], v[156:159], v[190:193], 0
	v_mfma_f32_16x16x32_bf16 v[58:61], v[152:155], v[186:189], v[58:61]
	v_mfma_f32_16x16x32_bf16 v[42:45], v[152:155], v[194:197], 0
	v_mfma_f32_16x16x32_bf16 v[42:45], v[156:159], v[198:201], v[42:45]
	v_mfma_f32_16x16x32_bf16 v[46:49], v[134:137], v[198:201], 0
	v_mfma_f32_16x16x32_bf16 v[46:49], v[130:133], v[194:197], v[46:49]
	v_mfma_f32_16x16x32_bf16 v[30:33], v[130:133], v[202:205], 0
	v_mfma_f32_16x16x32_bf16 v[30:33], v[134:137], v[206:209], v[30:33]
	v_mfma_f32_16x16x32_bf16 v[26:29], v[156:159], v[206:209], 0
	v_mfma_f32_16x16x32_bf16 v[26:29], v[152:155], v[202:205], v[26:29]
	v_mfma_f32_16x16x32_bf16 v[10:13], v[152:155], v[210:213], 0
	v_mfma_f32_16x16x32_bf16 v[10:13], v[156:159], v[214:217], v[10:13]
	v_mfma_f32_16x16x32_bf16 v[14:17], v[134:137], v[214:217], 0
	v_mfma_f32_16x16x32_bf16 v[14:17], v[130:133], v[210:213], v[14:17]
	s_setprio 0
	s_setprio 1
	v_mfma_f32_16x16x32_bf16 v[6:9], v[166:169], v[210:213], 0
	v_mfma_f32_16x16x32_bf16 v[6:9], v[170:173], v[214:217], v[6:9]
	v_mfma_f32_16x16x32_bf16 v[2:5], v[182:185], v[214:217], 0
	v_mfma_f32_16x16x32_bf16 v[2:5], v[174:177], v[210:213], v[2:5]
	v_mfma_f32_16x16x32_bf16 v[18:21], v[174:177], v[202:205], 0
	v_mfma_f32_16x16x32_bf16 v[18:21], v[182:185], v[206:209], v[18:21]
	v_mfma_f32_16x16x32_bf16 v[22:25], v[170:173], v[206:209], 0
	v_mfma_f32_16x16x32_bf16 v[22:25], v[166:169], v[202:205], v[22:25]
	v_mfma_f32_16x16x32_bf16 v[38:41], v[166:169], v[194:197], 0
	v_mfma_f32_16x16x32_bf16 v[38:41], v[170:173], v[198:201], v[38:41]
	v_mfma_f32_16x16x32_bf16 v[34:37], v[182:185], v[198:201], 0
	v_mfma_f32_16x16x32_bf16 v[34:37], v[174:177], v[194:197], v[34:37]
	v_mfma_f32_16x16x32_bf16 v[50:53], v[174:177], v[186:189], 0
	v_mfma_f32_16x16x32_bf16 v[50:53], v[182:185], v[190:193], v[50:53]
	v_mfma_f32_16x16x32_bf16 v[54:57], v[170:173], v[190:193], 0
	v_mfma_f32_16x16x32_bf16 v[54:57], v[166:169], v[186:189], v[54:57]
	s_setprio 0
	s_barrier
	s_add_i32 s90, 0, 0x18000
	v_add_u32_e32 v143, s90, v160
	s_add_i32 s91, 0, 0x1c000
	ds_read_b128 v[130:133], v143
	ds_read_b128 v[134:137], v143 offset:1024
	ds_read_b128 v[152:155], v143 offset:2048
	ds_read_b128 v[156:159], v143 offset:3072
	v_add_u32_e32 v143, s91, v160
	ds_read_b128 v[166:169], v143
	ds_read_b128 v[170:173], v143 offset:1024
	ds_read_b128 v[174:177], v143 offset:2048
	ds_read_b128 v[182:185], v143 offset:3072
	s_add_u32 s70, s70, 0x80000
	s_addc_u32 s71, s71, 0
	s_mov_b32 m0, s74
	v_lshl_add_u64 v[178:179], s[70:71], 0, v[138:139]
	ds_read_b128 v[186:189], v163 offset:32768
	ds_read_b128 v[190:193], v163 offset:33792
	ds_read_b128 v[194:197], v163 offset:34816
	ds_read_b128 v[198:201], v163 offset:35840
	ds_read_b128 v[202:205], v163 offset:36864
	ds_read_b128 v[206:209], v163 offset:37888
	ds_read_b128 v[210:213], v163 offset:38912
	ds_read_b128 v[214:217], v163 offset:39936
	global_load_lds_dwordx4 v[178:179], off
	v_lshl_add_u64 v[178:179], s[70:71], 0, v[140:141]
	s_mov_b32 m0, s75
	s_nop 0
	global_load_lds_dwordx4 v[178:179], off
	s_waitcnt vmcnt(8)
	s_waitcnt lgkmcnt(0)
	s_barrier
	s_setprio 1
	s_waitcnt lgkmcnt(0)
	v_mfma_f32_16x16x32_bf16 v[126:129], v[130:133], v[186:189], v[126:129]
	v_mfma_f32_16x16x32_bf16 v[126:129], v[134:137], v[190:193], v[126:129]
	v_mfma_f32_16x16x32_bf16 v[122:125], v[156:159], v[190:193], v[122:125]
	v_mfma_f32_16x16x32_bf16 v[122:125], v[152:155], v[186:189], v[122:125]
	v_mfma_f32_16x16x32_bf16 v[106:109], v[152:155], v[194:197], v[106:109]
	v_mfma_f32_16x16x32_bf16 v[106:109], v[156:159], v[198:201], v[106:109]
	v_mfma_f32_16x16x32_bf16 v[110:113], v[134:137], v[198:201], v[110:113]
	v_mfma_f32_16x16x32_bf16 v[110:113], v[130:133], v[194:197], v[110:113]
	v_mfma_f32_16x16x32_bf16 v[94:97], v[130:133], v[202:205], v[94:97]
	v_mfma_f32_16x16x32_bf16 v[94:97], v[134:137], v[206:209], v[94:97]
	v_mfma_f32_16x16x32_bf16 v[90:93], v[156:159], v[206:209], v[90:93]
	v_mfma_f32_16x16x32_bf16 v[90:93], v[152:155], v[202:205], v[90:93]
	v_mfma_f32_16x16x32_bf16 v[74:77], v[152:155], v[210:213], v[74:77]
	v_mfma_f32_16x16x32_bf16 v[74:77], v[156:159], v[214:217], v[74:77]
	v_mfma_f32_16x16x32_bf16 v[78:81], v[134:137], v[214:217], v[78:81]
	v_mfma_f32_16x16x32_bf16 v[78:81], v[130:133], v[210:213], v[78:81]
	s_setprio 0
	s_setprio 1
	v_mfma_f32_16x16x32_bf16 v[70:73], v[166:169], v[210:213], v[70:73]
	v_mfma_f32_16x16x32_bf16 v[70:73], v[170:173], v[214:217], v[70:73]
	v_mfma_f32_16x16x32_bf16 v[66:69], v[182:185], v[214:217], v[66:69]
	v_mfma_f32_16x16x32_bf16 v[66:69], v[174:177], v[210:213], v[66:69]
	v_mfma_f32_16x16x32_bf16 v[82:85], v[174:177], v[202:205], v[82:85]
	v_mfma_f32_16x16x32_bf16 v[82:85], v[182:185], v[206:209], v[82:85]
	v_mfma_f32_16x16x32_bf16 v[86:89], v[170:173], v[206:209], v[86:89]
	v_mfma_f32_16x16x32_bf16 v[86:89], v[166:169], v[202:205], v[86:89]
	v_mfma_f32_16x16x32_bf16 v[102:105], v[166:169], v[194:197], v[102:105]
	v_mfma_f32_16x16x32_bf16 v[102:105], v[170:173], v[198:201], v[102:105]
	v_mfma_f32_16x16x32_bf16 v[98:101], v[182:185], v[198:201], v[98:101]
	v_mfma_f32_16x16x32_bf16 v[98:101], v[174:177], v[194:197], v[98:101]
	v_mfma_f32_16x16x32_bf16 v[114:117], v[174:177], v[186:189], v[114:117]
	v_mfma_f32_16x16x32_bf16 v[114:117], v[182:185], v[190:193], v[114:117]
	v_mfma_f32_16x16x32_bf16 v[118:121], v[170:173], v[190:193], v[118:121]
	v_mfma_f32_16x16x32_bf16 v[118:121], v[166:169], v[186:189], v[118:121]
	s_setprio 0
	s_barrier
; #define PG8_LAS __attribute__((address_space(3)))
; #define PG8_WAIT_V(n) asm volatile("s_waitcnt vmcnt(" #n ")" ::: "memory")
; #define PG8_BAR __builtin_amdgcn_s_barrier()
; template <class Epi, class Sched, bool ALIGN_EPI = false, bool SP2 = false, bool RS = false, bool BPRE = false>
; __device__ __forceinline__ void gemm_phase(PG8_LAS unsigned char* lds, const Gemm g, const Sched& S, const Epi& E, const float* rs_ss = nullptr, PG8_LAS float* rs_tab = nullptr) {
;     ...
;         for (int t = 0; t < nt; t += 2) {
;             const bool last = (t == nt - 2);
;             if constexpr (RS) { if (t == 16 || t == 32) { const PG8_LAS float* tp = rs_tab + (ui & 1) * 768 + (t == 32 ? 256 : 0);
;                 _Pragma("unroll") for (int a = 0; a < 2; ++a) _Pragma("unroll") for (int m = 0; m < 4; ++m) { const float f = tp[a * HALF + wr * 64 + m * 16 + fr];
;                     _Pragma("unroll") for (int b = 0; b < 2; ++b) _Pragma("unroll") for (int n = 0; n < 2; ++n) acc[a][b][m][n] = acc[a][b][m][n] * f; } } }
;             const char* a1 = cA + (size_t)(t + 1) * kstep;
;             const char* a2 = last ? nA : cA + (size_t)(t + 2) * kstep; const char* b2 = last ? nB : cB + (size_t)(t + 2) * kstep;
;             const char* a3 = a2 + kstep; const char* b3 = b2 + kstep;
;             if (last && has_next) S.a_ready(nxt);
;             if constexpr (SP2) {
;             PG8_LDB(B0, 0, 0); PG8_LDB(B1, 0, 1); PG8_SCHED; PG8_LDA(At, 0, 0); PG8_STAGE(PG8_SA(1, 1), a1 + hstep, voffA);
;             PG8_WAIT_V(8); PG8_WAIT_L(0); PG8_BAR; PG8_MMA(0, 0, At, B0); PG8_MMA(0, 1, At, B1); PG8_BAR; PG8_SCHED;
;             PG8_LDA(At, 0, 1); PG8_STAGE(PG8_SB(0, 0), b2, voffB); PG8_STAGE(PG8_SB(0, 1), b2 + hstep, voffB); PG8_STAGE(PG8_SA(0, 0), a2, voffA);
;             PG8_WAIT_V(8); PG8_WAIT_L(0); PG8_BAR; PG8_MMA(1, 0, At, B0); PG8_MMA(1, 1, At, B1); PG8_BAR; PG8_SCHED;
;             PG8_LDB(B0, 1, 0); PG8_LDB(B1, 1, 1); PG8_SCHED; PG8_LDA(At, 1, 0); PG8_STAGE(PG8_SA(0, 1), a2 + hstep, voffA);
;             PG8_WAIT_V(8); PG8_WAIT_L(0); PG8_BAR; PG8_MMA(0, 0, At, B0); PG8_MMA(0, 1, At, B1); PG8_BAR; PG8_SCHED;
;             PG8_LDA(At, 1, 1); PG8_STAGE(PG8_SB(1, 0), b3, voffB); PG8_STAGE(PG8_SB(1, 1), b3 + hstep, voffB); PG8_STAGE(PG8_SA(1, 0), a3, voffA);
;             PG8_WAIT_V(8); PG8_WAIT_L(0); PG8_BAR; PG8_MMA(1, 0, At, B0); PG8_MMA(1, 1, At, B1); PG8_BAR; PG8_SCHED;
	s_add_u32 s70, s60, 0x4000
	s_addc_u32 s71, s61, 0
	s_add_i32 s90, s90, s15
	v_lshl_add_u64 v[178:179], s[70:71], 0, v[138:139]
	s_mov_b32 m0, s90
	ds_read_b128 v[186:189], v163 offset:49152
	ds_read_b128 v[190:193], v163 offset:50176
	ds_read_b128 v[194:197], v163 offset:51200
	ds_read_b128 v[198:201], v163 offset:52224
	ds_read_b128 v[202:205], v163 offset:53248
	ds_read_b128 v[206:209], v163 offset:54272
	ds_read_b128 v[210:213], v163 offset:55296
	ds_read_b128 v[214:217], v163 offset:56320
	global_load_lds_dwordx4 v[178:179], off
	s_add_i32 m0, s90, 0x2000
	s_add_u32 s60, s60, 0x84000
	v_lshl_add_u64 v[178:179], s[70:71], 0, v[140:141]
	s_addc_u32 s61, s61, 0
	s_add_i32 s70, s91, s15
	global_load_lds_dwordx4 v[178:179], off
	v_lshl_add_u64 v[178:179], s[60:61], 0, v[138:139]
	s_mov_b32 m0, s70
	s_nop 0
	global_load_lds_dwordx4 v[178:179], off
	v_lshl_add_u64 v[178:179], s[60:61], 0, v[140:141]
	s_add_i32 m0, s70, 0x2000
	s_nop 0
	global_load_lds_dwordx4 v[178:179], off
	v_lshl_add_u64 v[178:179], s[58:59], 0, v[138:139]
	s_mov_b32 m0, s79
	s_nop 0
	global_load_lds_dwordx4 v[178:179], off
	v_lshl_add_u64 v[178:179], s[58:59], 0, v[140:141]
	s_mov_b32 m0, s80
	s_nop 0
	global_load_lds_dwordx4 v[178:179], off
	s_waitcnt vmcnt(8)
	s_waitcnt lgkmcnt(0)
	s_barrier
	s_setprio 1
	s_waitcnt lgkmcnt(0)
	v_mfma_f32_16x16x32_bf16 v[62:65], v[130:133], v[186:189], v[62:65]
	v_mfma_f32_16x16x32_bf16 v[62:65], v[134:137], v[190:193], v[62:65]
	v_mfma_f32_16x16x32_bf16 v[58:61], v[156:159], v[190:193], v[58:61]
	v_mfma_f32_16x16x32_bf16 v[58:61], v[152:155], v[186:189], v[58:61]
	v_mfma_f32_16x16x32_bf16 v[42:45], v[152:155], v[194:197], v[42:45]
	v_mfma_f32_16x16x32_bf16 v[42:45], v[156:159], v[198:201], v[42:45]
	v_mfma_f32_16x16x32_bf16 v[46:49], v[134:137], v[198:201], v[46:49]
	v_mfma_f32_16x16x32_bf16 v[46:49], v[130:133], v[194:197], v[46:49]
	v_mfma_f32_16x16x32_bf16 v[30:33], v[130:133], v[202:205], v[30:33]
	v_mfma_f32_16x16x32_bf16 v[30:33], v[134:137], v[206:209], v[30:33]
	v_mfma_f32_16x16x32_bf16 v[26:29], v[156:159], v[206:209], v[26:29]
	v_mfma_f32_16x16x32_bf16 v[26:29], v[152:155], v[202:205], v[26:29]
	v_mfma_f32_16x16x32_bf16 v[10:13], v[152:155], v[210:213], v[10:13]
	v_mfma_f32_16x16x32_bf16 v[10:13], v[156:159], v[214:217], v[10:13]
	v_mfma_f32_16x16x32_bf16 v[14:17], v[134:137], v[214:217], v[14:17]
	v_mfma_f32_16x16x32_bf16 v[14:17], v[130:133], v[210:213], v[14:17]
	s_setprio 0
	s_setprio 1
	v_mfma_f32_16x16x32_bf16 v[6:9], v[166:169], v[210:213], v[6:9]
	v_mfma_f32_16x16x32_bf16 v[6:9], v[170:173], v[214:217], v[6:9]
	v_mfma_f32_16x16x32_bf16 v[2:5], v[182:185], v[214:217], v[2:5]
	v_mfma_f32_16x16x32_bf16 v[2:5], v[174:177], v[210:213], v[2:5]
	v_mfma_f32_16x16x32_bf16 v[18:21], v[174:177], v[202:205], v[18:21]
	v_mfma_f32_16x16x32_bf16 v[18:21], v[182:185], v[206:209], v[18:21]
	v_mfma_f32_16x16x32_bf16 v[22:25], v[170:173], v[206:209], v[22:25]
	v_mfma_f32_16x16x32_bf16 v[22:25], v[166:169], v[202:205], v[22:25]
	v_mfma_f32_16x16x32_bf16 v[38:41], v[166:169], v[194:197], v[38:41]
	v_mfma_f32_16x16x32_bf16 v[38:41], v[170:173], v[198:201], v[38:41]
	v_mfma_f32_16x16x32_bf16 v[34:37], v[182:185], v[198:201], v[34:37]
	v_mfma_f32_16x16x32_bf16 v[34:37], v[174:177], v[194:197], v[34:37]
	v_mfma_f32_16x16x32_bf16 v[50:53], v[174:177], v[186:189], v[50:53]
	v_mfma_f32_16x16x32_bf16 v[50:53], v[182:185], v[190:193], v[50:53]
	v_mfma_f32_16x16x32_bf16 v[54:57], v[170:173], v[190:193], v[54:57]
	v_mfma_f32_16x16x32_bf16 v[54:57], v[166:169], v[186:189], v[54:57]
	s_setprio 0
	s_barrier
	s_add_i32 s89, s89, 2
	s_add_u32 s56, s56, 0x8000
	s_addc_u32 s57, s57, 0
	s_add_u32 s87, s87, 0x8000
	s_addc_u32 s88, s88, 0
.LBB0_196:
	ds_read_b128 v[130:133], v161
	ds_read_b128 v[134:137], v161 offset:1024
	ds_read_b128 v[152:155], v161 offset:2048
	ds_read_b128 v[156:159], v161 offset:3072
	ds_read_b128 v[166:169], v162
	ds_read_b128 v[170:173], v162 offset:1024
	ds_read_b128 v[174:177], v162 offset:2048
	ds_read_b128 v[182:185], v162 offset:3072
	s_add_u32 s58, s56, 0xfff84000
	s_addc_u32 s59, s57, -1
	s_cmp_eq_u32 s89, 28
	s_cselect_b32 s70, s19, s58
	s_cselect_b32 s71, s5, s59
	s_cselect_b32 s60, s47, s87
	s_cselect_b32 s61, s17, s88
	s_add_u32 s58, s70, 0x4000
	s_addc_u32 s59, s71, 0
	v_lshl_add_u64 v[178:179], s[56:57], 0, v[138:139]
	s_add_i32 m0, s72, 0xc000
	ds_read_b128 v[186:189], v163
	ds_read_b128 v[190:193], v163 offset:1024
	ds_read_b128 v[194:197], v163 offset:2048
	ds_read_b128 v[198:201], v163 offset:3072
	ds_read_b128 v[202:205], v163 offset:4096
	ds_read_b128 v[206:209], v163 offset:5120
	ds_read_b128 v[210:213], v163 offset:6144
	ds_read_b128 v[214:217], v163 offset:7168
	global_load_lds_dwordx4 v[178:179], off
	v_lshl_add_u64 v[178:179], s[56:57], 0, v[146:147]
	s_add_i32 m0, s72, 0xe000
	s_nop 0
	global_load_lds_dwordx4 v[178:179], off
	s_waitcnt vmcnt(8)
	s_waitcnt lgkmcnt(0)
	s_barrier
; #define PG8_STAGE(bufoff, gbase, voff) do { _Pragma("unroll") for (int _i = 0; _i < 2; ++_i) \
;         __builtin_amdgcn_global_load_lds((const unsigned*)((const char*)(gbase) + (voff)[_i]), (PG8_LAS unsigned*)(lds + (bufoff) + ldsw + _i * 8192), 16, 0, 0); } while (0)
; #define PG8_LDA(dst, b, h) do { _Pragma("unroll") for (int m = 0; m < 4; ++m) _Pragma("unroll") for (int k = 0; k < 2; ++k) dst[m][k] = *(const PG8_LAS bf16x8*)(lds + PG8_SA(b, h) + aoff + m * 2048 + k * 1024); } while (0)
; #define PG8_LDB(dst, b, h) do { _Pragma("unroll") for (int n = 0; n < 2; ++n) _Pragma("unroll") for (int k = 0; k < 2; ++k) dst[n][k] = *(const PG8_LAS bf16x8*)(lds + PG8_SB(b, h) + boff + n * 2048 + k * 1024); } while (0)
; #define PG8_MMA(ai, bj, At, Bt) do { __builtin_amdgcn_s_setprio(1); _Pragma("unroll") for (int m = 0; m < 4; ++m) _Pragma("unroll") for (int n = 0; n < 2; ++n) _Pragma("unroll") for (int k = 0; k < 2; ++k) \
;         acc[ai][bj][m][n] = __builtin_amdgcn_mfma_f32_16x16x32_bf16(Bt[n][k], At[m][k], acc[ai][bj][m][n], 0, 0, 0); __builtin_amdgcn_s_setprio(0); } while (0)
; #define PG8_WAIT_V(n) asm volatile("s_waitcnt vmcnt(" #n ")" ::: "memory")
; #define PG8_WAIT_L(n) asm volatile("s_waitcnt lgkmcnt(" #n ")" ::: "memory")
; #define PG8_BAR __builtin_amdgcn_s_barrier()
; #define PG8_SCHED __builtin_amdgcn_sched_barrier(0)
; template <class Epi, class Sched, bool ALIGN_EPI = false, bool SP2 = false, bool RS = false, bool BPRE = false>
; __device__ __forceinline__ void gemm_phase(PG8_LAS unsigned char* lds, const Gemm g, const Sched& S, const Epi& E, const float* rs_ss = nullptr, PG8_LAS float* rs_tab = nullptr) {
;     ...
;             PG8_LDB(B0, 0, 0); PG8_LDB(B1, 0, 1); PG8_SCHED; PG8_LDA(At, 0, 0); PG8_STAGE(PG8_SA(1, 1), a1 + hstep, voffA);
;             PG8_WAIT_V(8); PG8_WAIT_L(0); PG8_BAR; PG8_MMA(0, 0, At, B0); PG8_MMA(0, 1, At, B1); PG8_BAR; PG8_SCHED;
;             PG8_LDA(At, 0, 1); PG8_STAGE(PG8_SB(0, 0), b2, voffB); PG8_STAGE(PG8_SB(0, 1), b2 + hstep, voffB); PG8_STAGE(PG8_SA(0, 0), a2, voffA);
;             PG8_WAIT_V(8); PG8_WAIT_L(0); PG8_BAR; PG8_MMA(1, 0, At, B0); PG8_MMA(1, 1, At, B1); PG8_BAR; PG8_SCHED;
	s_setprio 1
	s_waitcnt lgkmcnt(0)
	v_mfma_f32_16x16x32_bf16 v[126:129], v[130:133], v[186:189], v[126:129]
	v_mfma_f32_16x16x32_bf16 v[126:129], v[134:137], v[190:193], v[126:129]
	v_mfma_f32_16x16x32_bf16 v[122:125], v[156:159], v[190:193], v[122:125]
	v_mfma_f32_16x16x32_bf16 v[122:125], v[152:155], v[186:189], v[122:125]
	v_mfma_f32_16x16x32_bf16 v[106:109], v[152:155], v[194:197], v[106:109]
	v_mfma_f32_16x16x32_bf16 v[106:109], v[156:159], v[198:201], v[106:109]
	v_mfma_f32_16x16x32_bf16 v[110:113], v[134:137], v[198:201], v[110:113]
	v_mfma_f32_16x16x32_bf16 v[110:113], v[130:133], v[194:197], v[110:113]
	v_mfma_f32_16x16x32_bf16 v[94:97], v[130:133], v[202:205], v[94:97]
	v_mfma_f32_16x16x32_bf16 v[94:97], v[134:137], v[206:209], v[94:97]
	v_mfma_f32_16x16x32_bf16 v[90:93], v[156:159], v[206:209], v[90:93]
	v_mfma_f32_16x16x32_bf16 v[90:93], v[152:155], v[202:205], v[90:93]
	v_mfma_f32_16x16x32_bf16 v[74:77], v[152:155], v[210:213], v[74:77]
	v_mfma_f32_16x16x32_bf16 v[74:77], v[156:159], v[214:217], v[74:77]
	v_mfma_f32_16x16x32_bf16 v[78:81], v[134:137], v[214:217], v[78:81]
	v_mfma_f32_16x16x32_bf16 v[78:81], v[130:133], v[210:213], v[78:81]
	s_setprio 0
	s_setprio 1
	v_mfma_f32_16x16x32_bf16 v[70:73], v[166:169], v[210:213], v[70:73]
	v_mfma_f32_16x16x32_bf16 v[70:73], v[170:173], v[214:217], v[70:73]
	v_mfma_f32_16x16x32_bf16 v[66:69], v[182:185], v[214:217], v[66:69]
	v_mfma_f32_16x16x32_bf16 v[66:69], v[174:177], v[210:213], v[66:69]
	v_mfma_f32_16x16x32_bf16 v[82:85], v[174:177], v[202:205], v[82:85]
	v_mfma_f32_16x16x32_bf16 v[82:85], v[182:185], v[206:209], v[82:85]
	v_mfma_f32_16x16x32_bf16 v[86:89], v[170:173], v[206:209], v[86:89]
	v_mfma_f32_16x16x32_bf16 v[86:89], v[166:169], v[202:205], v[86:89]
	v_mfma_f32_16x16x32_bf16 v[102:105], v[166:169], v[194:197], v[102:105]
	v_mfma_f32_16x16x32_bf16 v[102:105], v[170:173], v[198:201], v[102:105]
	v_mfma_f32_16x16x32_bf16 v[98:101], v[182:185], v[198:201], v[98:101]
	v_mfma_f32_16x16x32_bf16 v[98:101], v[174:177], v[194:197], v[98:101]
	v_mfma_f32_16x16x32_bf16 v[114:117], v[174:177], v[186:189], v[114:117]
	v_mfma_f32_16x16x32_bf16 v[114:117], v[182:185], v[190:193], v[114:117]
	v_mfma_f32_16x16x32_bf16 v[118:121], v[170:173], v[190:193], v[118:121]
	v_mfma_f32_16x16x32_bf16 v[118:121], v[166:169], v[186:189], v[118:121]
	s_setprio 0
	s_barrier
	s_add_i32 s90, s83, s15
	v_lshl_add_u64 v[178:179], s[60:61], 0, v[138:139]
	s_mov_b32 m0, s90
	ds_read_b128 v[186:189], v163 offset:16384
	ds_read_b128 v[190:193], v163 offset:17408
	ds_read_b128 v[194:197], v163 offset:18432
	ds_read_b128 v[198:201], v163 offset:19456
	ds_read_b128 v[202:205], v163 offset:20480
	ds_read_b128 v[206:209], v163 offset:21504
	ds_read_b128 v[210:213], v163 offset:22528
	ds_read_b128 v[214:217], v163 offset:23552
	global_load_lds_dwordx4 v[178:179], off
	s_add_i32 m0, s90, 0x2000
	s_add_u32 s90, s60, 0x80000
	v_lshl_add_u64 v[178:179], s[60:61], 0, v[140:141]
	s_addc_u32 s91, s61, 0
	s_add_i32 s92, s86, s15
	global_load_lds_dwordx4 v[178:179], off
	v_lshl_add_u64 v[178:179], s[90:91], 0, v[138:139]
	s_mov_b32 m0, s92
	s_nop 0
	global_load_lds_dwordx4 v[178:179], off
	v_lshl_add_u64 v[178:179], s[90:91], 0, v[140:141]
	s_add_i32 m0, s92, 0x2000
	s_nop 0
	global_load_lds_dwordx4 v[178:179], off
	v_lshl_add_u64 v[178:179], s[70:71], 0, v[138:139]
	s_mov_b32 m0, s72
	s_nop 0
	global_load_lds_dwordx4 v[178:179], off
	v_lshl_add_u64 v[178:179], s[70:71], 0, v[140:141]
	s_mov_b32 m0, s73
	s_nop 0
	global_load_lds_dwordx4 v[178:179], off
	s_waitcnt vmcnt(8)
	s_waitcnt lgkmcnt(0)
	s_barrier
	s_setprio 1
	s_waitcnt lgkmcnt(0)
	v_mfma_f32_16x16x32_bf16 v[62:65], v[130:133], v[186:189], v[62:65]
	v_mfma_f32_16x16x32_bf16 v[62:65], v[134:137], v[190:193], v[62:65]
	v_mfma_f32_16x16x32_bf16 v[58:61], v[156:159], v[190:193], v[58:61]
	v_mfma_f32_16x16x32_bf16 v[58:61], v[152:155], v[186:189], v[58:61]
	v_mfma_f32_16x16x32_bf16 v[42:45], v[152:155], v[194:197], v[42:45]
	v_mfma_f32_16x16x32_bf16 v[42:45], v[156:159], v[198:201], v[42:45]
	v_mfma_f32_16x16x32_bf16 v[46:49], v[134:137], v[198:201], v[46:49]
	v_mfma_f32_16x16x32_bf16 v[46:49], v[130:133], v[194:197], v[46:49]
	v_mfma_f32_16x16x32_bf16 v[30:33], v[130:133], v[202:205], v[30:33]
	v_mfma_f32_16x16x32_bf16 v[30:33], v[134:137], v[206:209], v[30:33]
	v_mfma_f32_16x16x32_bf16 v[26:29], v[156:159], v[206:209], v[26:29]
	v_mfma_f32_16x16x32_bf16 v[26:29], v[152:155], v[202:205], v[26:29]
	v_mfma_f32_16x16x32_bf16 v[10:13], v[152:155], v[210:213], v[10:13]
	v_mfma_f32_16x16x32_bf16 v[10:13], v[156:159], v[214:217], v[10:13]
	v_mfma_f32_16x16x32_bf16 v[14:17], v[134:137], v[214:217], v[14:17]
	v_mfma_f32_16x16x32_bf16 v[14:17], v[130:133], v[210:213], v[14:17]
	s_setprio 0
	s_setprio 1
	v_mfma_f32_16x16x32_bf16 v[6:9], v[166:169], v[210:213], v[6:9]
	v_mfma_f32_16x16x32_bf16 v[6:9], v[170:173], v[214:217], v[6:9]
	v_mfma_f32_16x16x32_bf16 v[2:5], v[182:185], v[214:217], v[2:5]
	v_mfma_f32_16x16x32_bf16 v[2:5], v[174:177], v[210:213], v[2:5]
	v_mfma_f32_16x16x32_bf16 v[18:21], v[174:177], v[202:205], v[18:21]
	v_mfma_f32_16x16x32_bf16 v[18:21], v[182:185], v[206:209], v[18:21]
	v_mfma_f32_16x16x32_bf16 v[22:25], v[170:173], v[206:209], v[22:25]
	v_mfma_f32_16x16x32_bf16 v[22:25], v[166:169], v[202:205], v[22:25]
	v_mfma_f32_16x16x32_bf16 v[38:41], v[166:169], v[194:197], v[38:41]
	v_mfma_f32_16x16x32_bf16 v[38:41], v[170:173], v[198:201], v[38:41]
	v_mfma_f32_16x16x32_bf16 v[34:37], v[182:185], v[198:201], v[34:37]
	v_mfma_f32_16x16x32_bf16 v[34:37], v[174:177], v[194:197], v[34:37]
	v_mfma_f32_16x16x32_bf16 v[50:53], v[174:177], v[186:189], v[50:53]
	v_mfma_f32_16x16x32_bf16 v[50:53], v[182:185], v[190:193], v[50:53]
	v_mfma_f32_16x16x32_bf16 v[54:57], v[170:173], v[190:193], v[54:57]
	v_mfma_f32_16x16x32_bf16 v[54:57], v[166:169], v[186:189], v[54:57]
	s_setprio 0
	s_barrier
; #define PG8_STAGE(bufoff, gbase, voff) do { _Pragma("unroll") for (int _i = 0; _i < 2; ++_i) \
;         __builtin_amdgcn_global_load_lds((const unsigned*)((const char*)(gbase) + (voff)[_i]), (PG8_LAS unsigned*)(lds + (bufoff) + ldsw + _i * 8192), 16, 0, 0); } while (0)
; #define PG8_LDA(dst, b, h) do { _Pragma("unroll") for (int m = 0; m < 4; ++m) _Pragma("unroll") for (int k = 0; k < 2; ++k) dst[m][k] = *(const PG8_LAS bf16x8*)(lds + PG8_SA(b, h) + aoff + m * 2048 + k * 1024); } while (0)
; #define PG8_LDB(dst, b, h) do { _Pragma("unroll") for (int n = 0; n < 2; ++n) _Pragma("unroll") for (int k = 0; k < 2; ++k) dst[n][k] = *(const PG8_LAS bf16x8*)(lds + PG8_SB(b, h) + boff + n * 2048 + k * 1024); } while (0)
; #define PG8_MMA(ai, bj, At, Bt) do { __builtin_amdgcn_s_setprio(1); _Pragma("unroll") for (int m = 0; m < 4; ++m) _Pragma("unroll") for (int n = 0; n < 2; ++n) _Pragma("unroll") for (int k = 0; k < 2; ++k) \
;         acc[ai][bj][m][n] = __builtin_amdgcn_mfma_f32_16x16x32_bf16(Bt[n][k], At[m][k], acc[ai][bj][m][n], 0, 0, 0); __builtin_amdgcn_s_setprio(0); } while (0)
; #define PG8_WAIT_V(n) asm volatile("s_waitcnt vmcnt(" #n ")" ::: "memory")
; #define PG8_WAIT_L(n) asm volatile("s_waitcnt lgkmcnt(" #n ")" ::: "memory")
; #define PG8_BAR __builtin_amdgcn_s_barrier()
; #define PG8_SCHED __builtin_amdgcn_sched_barrier(0)
; template <class Epi, class Sched, bool ALIGN_EPI = false, bool SP2 = false, bool RS = false, bool BPRE = false>
; __device__ __forceinline__ void gemm_phase(PG8_LAS unsigned char* lds, const Gemm g, const Sched& S, const Epi& E, const float* rs_ss = nullptr, PG8_LAS float* rs_tab = nullptr) {
;     ...
;             PG8_LDB(B0, 1, 0); PG8_LDB(B1, 1, 1); PG8_SCHED; PG8_LDA(At, 1, 0); PG8_STAGE(PG8_SA(0, 1), a2 + hstep, voffA);
;             PG8_WAIT_V(8); PG8_WAIT_L(0); PG8_BAR; PG8_MMA(0, 0, At, B0); PG8_MMA(0, 1, At, B1); PG8_BAR; PG8_SCHED;
	s_add_i32 s90, 0, 0x18000
	v_add_u32_e32 v143, s90, v160
	s_add_i32 s91, 0, 0x1c000
	ds_read_b128 v[130:133], v143
	ds_read_b128 v[134:137], v143 offset:1024
	ds_read_b128 v[152:155], v143 offset:2048
	ds_read_b128 v[156:159], v143 offset:3072
	v_add_u32_e32 v143, s91, v160
	ds_read_b128 v[166:169], v143
	ds_read_b128 v[170:173], v143 offset:1024
	ds_read_b128 v[174:177], v143 offset:2048
	ds_read_b128 v[182:185], v143 offset:3072
	s_add_u32 s70, s70, 0x80000
	s_addc_u32 s71, s71, 0
	s_mov_b32 m0, s74
	v_lshl_add_u64 v[178:179], s[70:71], 0, v[138:139]
	ds_read_b128 v[186:189], v163 offset:32768
	ds_read_b128 v[190:193], v163 offset:33792
	ds_read_b128 v[194:197], v163 offset:34816
	ds_read_b128 v[198:201], v163 offset:35840
	ds_read_b128 v[202:205], v163 offset:36864
	ds_read_b128 v[206:209], v163 offset:37888
	ds_read_b128 v[210:213], v163 offset:38912
	ds_read_b128 v[214:217], v163 offset:39936
	global_load_lds_dwordx4 v[178:179], off
	v_lshl_add_u64 v[178:179], s[70:71], 0, v[140:141]
	s_mov_b32 m0, s75
	s_nop 0
	global_load_lds_dwordx4 v[178:179], off
	s_waitcnt vmcnt(8)
	s_waitcnt lgkmcnt(0)
	s_barrier
	s_setprio 1
	s_waitcnt lgkmcnt(0)
	v_mfma_f32_16x16x32_bf16 v[126:129], v[130:133], v[186:189], v[126:129]
	v_mfma_f32_16x16x32_bf16 v[126:129], v[134:137], v[190:193], v[126:129]
	v_mfma_f32_16x16x32_bf16 v[122:125], v[156:159], v[190:193], v[122:125]
	v_mfma_f32_16x16x32_bf16 v[122:125], v[152:155], v[186:189], v[122:125]
	v_mfma_f32_16x16x32_bf16 v[106:109], v[152:155], v[194:197], v[106:109]
	v_mfma_f32_16x16x32_bf16 v[106:109], v[156:159], v[198:201], v[106:109]
	v_mfma_f32_16x16x32_bf16 v[110:113], v[134:137], v[198:201], v[110:113]
	v_mfma_f32_16x16x32_bf16 v[110:113], v[130:133], v[194:197], v[110:113]
	v_mfma_f32_16x16x32_bf16 v[94:97], v[130:133], v[202:205], v[94:97]
	v_mfma_f32_16x16x32_bf16 v[94:97], v[134:137], v[206:209], v[94:97]
	v_mfma_f32_16x16x32_bf16 v[90:93], v[156:159], v[206:209], v[90:93]
	v_mfma_f32_16x16x32_bf16 v[90:93], v[152:155], v[202:205], v[90:93]
	v_mfma_f32_16x16x32_bf16 v[74:77], v[152:155], v[210:213], v[74:77]
	v_mfma_f32_16x16x32_bf16 v[74:77], v[156:159], v[214:217], v[74:77]
	v_mfma_f32_16x16x32_bf16 v[78:81], v[134:137], v[214:217], v[78:81]
	v_mfma_f32_16x16x32_bf16 v[78:81], v[130:133], v[210:213], v[78:81]
	s_setprio 0
	s_setprio 1
	v_mfma_f32_16x16x32_bf16 v[70:73], v[166:169], v[210:213], v[70:73]
	v_mfma_f32_16x16x32_bf16 v[70:73], v[170:173], v[214:217], v[70:73]
	v_mfma_f32_16x16x32_bf16 v[66:69], v[182:185], v[214:217], v[66:69]
	v_mfma_f32_16x16x32_bf16 v[66:69], v[174:177], v[210:213], v[66:69]
	v_mfma_f32_16x16x32_bf16 v[82:85], v[174:177], v[202:205], v[82:85]
	v_mfma_f32_16x16x32_bf16 v[82:85], v[182:185], v[206:209], v[82:85]
	v_mfma_f32_16x16x32_bf16 v[86:89], v[170:173], v[206:209], v[86:89]
	v_mfma_f32_16x16x32_bf16 v[86:89], v[166:169], v[202:205], v[86:89]
	v_mfma_f32_16x16x32_bf16 v[102:105], v[166:169], v[194:197], v[102:105]
	v_mfma_f32_16x16x32_bf16 v[102:105], v[170:173], v[198:201], v[102:105]
	v_mfma_f32_16x16x32_bf16 v[98:101], v[182:185], v[198:201], v[98:101]
	v_mfma_f32_16x16x32_bf16 v[98:101], v[174:177], v[194:197], v[98:101]
	v_mfma_f32_16x16x32_bf16 v[114:117], v[174:177], v[186:189], v[114:117]
	v_mfma_f32_16x16x32_bf16 v[114:117], v[182:185], v[190:193], v[114:117]
	v_mfma_f32_16x16x32_bf16 v[118:121], v[170:173], v[190:193], v[118:121]
	v_mfma_f32_16x16x32_bf16 v[118:121], v[166:169], v[186:189], v[118:121]
	s_setprio 0
	s_barrier
; #define PG8_STAGE(bufoff, gbase, voff) do { _Pragma("unroll") for (int _i = 0; _i < 2; ++_i) \
;         __builtin_amdgcn_global_load_lds((const unsigned*)((const char*)(gbase) + (voff)[_i]), (PG8_LAS unsigned*)(lds + (bufoff) + ldsw + _i * 8192), 16, 0, 0); } while (0)
; #define PG8_LDA(dst, b, h) do { _Pragma("unroll") for (int m = 0; m < 4; ++m) _Pragma("unroll") for (int k = 0; k < 2; ++k) dst[m][k] = *(const PG8_LAS bf16x8*)(lds + PG8_SA(b, h) + aoff + m * 2048 + k * 1024); } while (0)
; #define PG8_MMA(ai, bj, At, Bt) do { __builtin_amdgcn_s_setprio(1); _Pragma("unroll") for (int m = 0; m < 4; ++m) _Pragma("unroll") for (int n = 0; n < 2; ++n) _Pragma("unroll") for (int k = 0; k < 2; ++k) \
;         acc[ai][bj][m][n] = __builtin_amdgcn_mfma_f32_16x16x32_bf16(Bt[n][k], At[m][k], acc[ai][bj][m][n], 0, 0, 0); __builtin_amdgcn_s_setprio(0); } while (0)
; #define PG8_WAIT_V(n) asm volatile("s_waitcnt vmcnt(" #n ")" ::: "memory")
; #define PG8_WAIT_L(n) asm volatile("s_waitcnt lgkmcnt(" #n ")" ::: "memory")
; #define PG8_BAR __builtin_amdgcn_s_barrier()
; #define PG8_SCHED __builtin_amdgcn_sched_barrier(0)
; template <class Epi, class Sched, bool ALIGN_EPI = false, bool SP2 = false, bool RS = false, bool BPRE = false>
; __device__ __forceinline__ void gemm_phase(PG8_LAS unsigned char* lds, const Gemm g, const Sched& S, const Epi& E, const float* rs_ss = nullptr, PG8_LAS float* rs_tab = nullptr) {
;     ...
;         for (int t = 0; t < nt; t += 2) {
;     ...
;             PG8_LDA(At, 1, 1); PG8_STAGE(PG8_SB(1, 0), b3, voffB); PG8_STAGE(PG8_SB(1, 1), b3 + hstep, voffB); PG8_STAGE(PG8_SA(1, 0), a3, voffA);
;             PG8_WAIT_V(8); PG8_WAIT_L(0); PG8_BAR; PG8_MMA(1, 0, At, B0); PG8_MMA(1, 1, At, B1); PG8_BAR; PG8_SCHED;
;     ...
;         if constexpr (ALIGN_EPI) { if (wr == 0) PG8_BAR; }
	s_add_u32 s70, s60, 0x4000
	s_addc_u32 s71, s61, 0
	s_add_i32 s90, s90, s15
	v_lshl_add_u64 v[178:179], s[70:71], 0, v[138:139]
	s_mov_b32 m0, s90
	ds_read_b128 v[186:189], v163 offset:49152
	ds_read_b128 v[190:193], v163 offset:50176
	ds_read_b128 v[194:197], v163 offset:51200
	ds_read_b128 v[198:201], v163 offset:52224
	ds_read_b128 v[202:205], v163 offset:53248
	ds_read_b128 v[206:209], v163 offset:54272
	ds_read_b128 v[210:213], v163 offset:55296
	ds_read_b128 v[214:217], v163 offset:56320
	global_load_lds_dwordx4 v[178:179], off
	s_add_i32 m0, s90, 0x2000
	s_add_u32 s60, s60, 0x84000
	v_lshl_add_u64 v[178:179], s[70:71], 0, v[140:141]
	s_addc_u32 s61, s61, 0
	s_add_i32 s70, s91, s15
	global_load_lds_dwordx4 v[178:179], off
	v_lshl_add_u64 v[178:179], s[60:61], 0, v[138:139]
	s_mov_b32 m0, s70
	s_nop 0
	global_load_lds_dwordx4 v[178:179], off
	v_lshl_add_u64 v[178:179], s[60:61], 0, v[140:141]
	s_add_i32 m0, s70, 0x2000
	s_nop 0
	global_load_lds_dwordx4 v[178:179], off
	v_lshl_add_u64 v[178:179], s[58:59], 0, v[138:139]
	s_mov_b32 m0, s79
	s_nop 0
	global_load_lds_dwordx4 v[178:179], off
	v_lshl_add_u64 v[178:179], s[58:59], 0, v[140:141]
	s_mov_b32 m0, s80
	s_nop 0
	global_load_lds_dwordx4 v[178:179], off
	s_waitcnt vmcnt(8)
	s_waitcnt lgkmcnt(0)
	s_barrier
	s_setprio 1
	s_waitcnt lgkmcnt(0)
	v_mfma_f32_16x16x32_bf16 v[62:65], v[130:133], v[186:189], v[62:65]
	v_mfma_f32_16x16x32_bf16 v[62:65], v[134:137], v[190:193], v[62:65]
	v_mfma_f32_16x16x32_bf16 v[58:61], v[156:159], v[190:193], v[58:61]
	v_mfma_f32_16x16x32_bf16 v[58:61], v[152:155], v[186:189], v[58:61]
	v_mfma_f32_16x16x32_bf16 v[42:45], v[152:155], v[194:197], v[42:45]
	v_mfma_f32_16x16x32_bf16 v[42:45], v[156:159], v[198:201], v[42:45]
	v_mfma_f32_16x16x32_bf16 v[46:49], v[134:137], v[198:201], v[46:49]
	v_mfma_f32_16x16x32_bf16 v[46:49], v[130:133], v[194:197], v[46:49]
	v_mfma_f32_16x16x32_bf16 v[30:33], v[130:133], v[202:205], v[30:33]
	v_mfma_f32_16x16x32_bf16 v[30:33], v[134:137], v[206:209], v[30:33]
	v_mfma_f32_16x16x32_bf16 v[26:29], v[156:159], v[206:209], v[26:29]
	v_mfma_f32_16x16x32_bf16 v[26:29], v[152:155], v[202:205], v[26:29]
	v_mfma_f32_16x16x32_bf16 v[10:13], v[152:155], v[210:213], v[10:13]
	v_mfma_f32_16x16x32_bf16 v[10:13], v[156:159], v[214:217], v[10:13]
	v_mfma_f32_16x16x32_bf16 v[14:17], v[134:137], v[214:217], v[14:17]
	v_mfma_f32_16x16x32_bf16 v[14:17], v[130:133], v[210:213], v[14:17]
	s_setprio 0
	s_setprio 1
	v_mfma_f32_16x16x32_bf16 v[6:9], v[166:169], v[210:213], v[6:9]
	v_mfma_f32_16x16x32_bf16 v[6:9], v[170:173], v[214:217], v[6:9]
	v_mfma_f32_16x16x32_bf16 v[2:5], v[182:185], v[214:217], v[2:5]
	v_mfma_f32_16x16x32_bf16 v[2:5], v[174:177], v[210:213], v[2:5]
	v_mfma_f32_16x16x32_bf16 v[18:21], v[174:177], v[202:205], v[18:21]
	v_mfma_f32_16x16x32_bf16 v[18:21], v[182:185], v[206:209], v[18:21]
	v_mfma_f32_16x16x32_bf16 v[22:25], v[170:173], v[206:209], v[22:25]
	v_mfma_f32_16x16x32_bf16 v[22:25], v[166:169], v[202:205], v[22:25]
	v_mfma_f32_16x16x32_bf16 v[38:41], v[166:169], v[194:197], v[38:41]
	v_mfma_f32_16x16x32_bf16 v[38:41], v[170:173], v[198:201], v[38:41]
	v_mfma_f32_16x16x32_bf16 v[34:37], v[182:185], v[198:201], v[34:37]
	v_mfma_f32_16x16x32_bf16 v[34:37], v[174:177], v[194:197], v[34:37]
	v_mfma_f32_16x16x32_bf16 v[50:53], v[174:177], v[186:189], v[50:53]
	v_mfma_f32_16x16x32_bf16 v[50:53], v[182:185], v[190:193], v[50:53]
	v_mfma_f32_16x16x32_bf16 v[54:57], v[170:173], v[190:193], v[54:57]
	v_mfma_f32_16x16x32_bf16 v[54:57], v[166:169], v[186:189], v[54:57]
	s_setprio 0
	s_barrier
	s_add_i32 s89, s89, 2
	s_add_u32 s56, s56, 0x8000
	s_addc_u32 s57, s57, 0
	s_add_u32 s87, s87, 0x8000
	s_addc_u32 s88, s88, 0
	s_cmp_gt_u32 s89, 29
	s_cbranch_scc0 .LBB0_196
	s_and_b64 vcc, exec, s[12:13]
	s_cbranch_vccz .LBB0_199
	s_barrier

; #define PG8_STAGE(bufoff, gbase, voff) do { _Pragma("unroll") for (int _i = 0; _i < 2; ++_i) \
;         __builtin_amdgcn_global_load_lds((const unsigned*)((const char*)(gbase) + (voff)[_i]), (PG8_LAS unsigned*)(lds + (bufoff) + ldsw + _i * 8192), 16, 0, 0); } while (0)
; #define PG8_LDA(dst, b, h) do { _Pragma("unroll") for (int m = 0; m < 4; ++m) _Pragma("unroll") for (int k = 0; k < 2; ++k) dst[m][k] = *(const PG8_LAS bf16x8*)(lds + PG8_SA(b, h) + aoff + m * 2048 + k * 1024); } while (0)
; #define PG8_LDB(dst, b, h) do { _Pragma("unroll") for (int n = 0; n < 2; ++n) _Pragma("unroll") for (int k = 0; k < 2; ++k) dst[n][k] = *(const PG8_LAS bf16x8*)(lds + PG8_SB(b, h) + boff + n * 2048 + k * 1024); } while (0)
; #define PG8_MMA(ai, bj, At, Bt) do { __builtin_amdgcn_s_setprio(1); _Pragma("unroll") for (int m = 0; m < 4; ++m) _Pragma("unroll") for (int n = 0; n < 2; ++n) _Pragma("unroll") for (int k = 0; k < 2; ++k) \
;         acc[ai][bj][m][n] = __builtin_amdgcn_mfma_f32_16x16x32_bf16(Bt[n][k], At[m][k], acc[ai][bj][m][n], 0, 0, 0); __builtin_amdgcn_s_setprio(0); } while (0)
; template <class Epi, class Sched, bool ALIGN_EPI = false, bool SP2 = false, bool RS = false, bool BPRE = false>
; __device__ __forceinline__ void gemm_phase(PG8_LAS unsigned char* lds, const Gemm g, const Sched& S, const Epi& E, const float* rs_ss = nullptr, PG8_LAS float* rs_tab = nullptr) {
;     ...
;             const char* a1 = cA + (size_t)(t + 1) * kstep;
;             const char* a2 = last ? nA : cA + (size_t)(t + 2) * kstep; const char* b2 = last ? nB : cB + (size_t)(t + 2) * kstep;
;             const char* a3 = a2 + kstep; const char* b3 = b2 + kstep;
;             if (last && has_next) S.a_ready(nxt);
;             if constexpr (SP2) {
;             PG8_LDB(B0, 0, 0); PG8_LDB(B1, 0, 1); PG8_SCHED; PG8_LDA(At, 0, 0); PG8_STAGE(PG8_SA(1, 1), a1 + hstep, voffA);
;             PG8_WAIT_V(8); PG8_WAIT_L(0); PG8_BAR; PG8_MMA(0, 0, At, B0); PG8_MMA(0, 1, At, B1); PG8_BAR; PG8_SCHED;
;             PG8_LDA(At, 0, 1); PG8_STAGE(PG8_SB(0, 0), b2, voffB); PG8_STAGE(PG8_SB(0, 1), b2 + hstep, voffB); PG8_STAGE(PG8_SA(0, 0), a2, voffA);
;             PG8_WAIT_V(8); PG8_WAIT_L(0); PG8_BAR; PG8_MMA(1, 0, At, B0); PG8_MMA(1, 1, At, B1); PG8_BAR; PG8_SCHED;
;     ...
;         if constexpr (!Epi::AFTER_DRAIN) { E(acc, cur, wr, wc, fr, fq, rs_tab + (ui & 1) * 768); S.done(cur); }
.LBB0_751:
	s_bitcmp1_b32 s40, 0
	v_mov_b32_e32 v4, v2
	v_mov_b32_e32 v5, v2
	s_cselect_b32 s6, 0xc00, 0
	s_add_u32 s71, s38, 0x8000
	v_mov_b32_e32 v3, v2
	s_waitcnt lgkmcnt(0)
	s_waitcnt vmcnt(0)
	s_mov_b32 s73, 0
	v_add_u32_e32 v158, s6, v151
	v_lshl_add_u64 v[146:147], s[10:11], 0, v[138:139]
	v_lshl_add_u64 v[148:149], s[10:11], 0, v[140:141]
	s_addc_u32 s72, s39, 0
	s_mov_b64 s[6:7], 0
	s_add_u32 s38, s10, s6
	v_add_u32_e32 v3, s64, v150
	s_addc_u32 s39, s11, s7
	ds_read_b128 v[160:163], v3
	ds_read_b128 v[164:167], v3 offset:1024
	ds_read_b128 v[168:171], v3 offset:2048
	ds_read_b128 v[172:175], v3 offset:3072
	v_add_u32_e32 v3, s65, v150
	s_add_u32 s38, s38, 0x8000
	ds_read_b128 v[176:179], v3
	ds_read_b128 v[180:183], v3 offset:1024
	ds_read_b128 v[184:187], v3 offset:2048
	ds_read_b128 v[188:191], v3 offset:3072
	s_addc_u32 s39, s39, 0
	s_add_u32 s40, s71, s6
	s_addc_u32 s41, s72, s7
	s_cmp_eq_u32 s6, 0xb8000
	s_cselect_b32 s42, s20, s38
	s_cselect_b32 s43, s21, s39
	s_cselect_b32 s40, s36, s40
	s_cselect_b32 s41, s37, s41
	s_add_u32 s38, s42, 0x4000
	s_addc_u32 s39, s43, 0
	v_lshl_add_u64 v[4:5], v[146:147], 0, s[6:7]
	s_add_i32 m0, s55, 0xc000
	ds_read_b128 v[192:195], v154
	ds_read_b128 v[196:199], v154 offset:1024
	ds_read_b128 v[200:203], v154 offset:2048
	ds_read_b128 v[204:207], v154 offset:3072
	ds_read_b128 v[208:211], v154 offset:4096
	ds_read_b128 v[212:215], v154 offset:5120
	ds_read_b128 v[216:219], v154 offset:6144
	ds_read_b128 v[220:223], v154 offset:7168
	global_load_lds_dwordx4 v[4:5], off
	v_lshl_add_u64 v[4:5], v[148:149], 0, s[6:7]
	s_add_i32 m0, s55, 0xe000
	s_nop 0
	global_load_lds_dwordx4 v[4:5], off
	s_waitcnt vmcnt(8)
	s_waitcnt lgkmcnt(0)
	s_barrier
	s_setprio 1
	s_waitcnt lgkmcnt(0)
	v_mfma_f32_16x16x32_bf16 v[130:133], v[160:163], v[192:195], 0
	v_mfma_f32_16x16x32_bf16 v[130:133], v[164:167], v[196:199], v[130:133]
	v_mfma_f32_16x16x32_bf16 v[126:129], v[172:175], v[196:199], 0
	v_mfma_f32_16x16x32_bf16 v[126:129], v[168:171], v[192:195], v[126:129]
	v_mfma_f32_16x16x32_bf16 v[110:113], v[168:171], v[200:203], 0
	v_mfma_f32_16x16x32_bf16 v[110:113], v[172:175], v[204:207], v[110:113]
	v_mfma_f32_16x16x32_bf16 v[114:117], v[164:167], v[204:207], 0
	v_mfma_f32_16x16x32_bf16 v[114:117], v[160:163], v[200:203], v[114:117]
	v_mfma_f32_16x16x32_bf16 v[98:101], v[160:163], v[208:211], 0
	v_mfma_f32_16x16x32_bf16 v[98:101], v[164:167], v[212:215], v[98:101]
	v_mfma_f32_16x16x32_bf16 v[94:97], v[172:175], v[212:215], 0
	v_mfma_f32_16x16x32_bf16 v[94:97], v[168:171], v[208:211], v[94:97]
	v_mfma_f32_16x16x32_bf16 v[78:81], v[168:171], v[216:219], 0
	v_mfma_f32_16x16x32_bf16 v[78:81], v[172:175], v[220:223], v[78:81]
	v_mfma_f32_16x16x32_bf16 v[82:85], v[164:167], v[220:223], 0
	v_mfma_f32_16x16x32_bf16 v[82:85], v[160:163], v[216:219], v[82:85]
	s_setprio 0
	s_setprio 1
	v_mfma_f32_16x16x32_bf16 v[74:77], v[176:179], v[216:219], 0
	v_mfma_f32_16x16x32_bf16 v[74:77], v[180:183], v[220:223], v[74:77]
	v_mfma_f32_16x16x32_bf16 v[70:73], v[188:191], v[220:223], 0
	v_mfma_f32_16x16x32_bf16 v[70:73], v[184:187], v[216:219], v[70:73]
	v_mfma_f32_16x16x32_bf16 v[86:89], v[184:187], v[208:211], 0
	v_mfma_f32_16x16x32_bf16 v[86:89], v[188:191], v[212:215], v[86:89]
	v_mfma_f32_16x16x32_bf16 v[90:93], v[180:183], v[212:215], 0
	v_mfma_f32_16x16x32_bf16 v[90:93], v[176:179], v[208:211], v[90:93]
	v_mfma_f32_16x16x32_bf16 v[106:109], v[176:179], v[200:203], 0
	v_mfma_f32_16x16x32_bf16 v[106:109], v[180:183], v[204:207], v[106:109]
	v_mfma_f32_16x16x32_bf16 v[102:105], v[188:191], v[204:207], 0
	v_mfma_f32_16x16x32_bf16 v[102:105], v[184:187], v[200:203], v[102:105]
	v_mfma_f32_16x16x32_bf16 v[118:121], v[184:187], v[192:195], 0
	v_mfma_f32_16x16x32_bf16 v[118:121], v[188:191], v[196:199], v[118:121]
	v_mfma_f32_16x16x32_bf16 v[122:125], v[180:183], v[196:199], 0
	v_mfma_f32_16x16x32_bf16 v[122:125], v[176:179], v[192:195], v[122:125]
	s_setprio 0
	s_barrier
	s_add_i32 s74, s64, s54
	v_lshl_add_u64 v[4:5], s[40:41], 0, v[134:135]
	s_mov_b32 m0, s74
	ds_read_b128 v[192:195], v154 offset:16384
	ds_read_b128 v[196:199], v154 offset:17408
	ds_read_b128 v[200:203], v154 offset:18432
	ds_read_b128 v[204:207], v154 offset:19456
	ds_read_b128 v[208:211], v154 offset:20480
	ds_read_b128 v[212:215], v154 offset:21504
	ds_read_b128 v[216:219], v154 offset:22528
	ds_read_b128 v[220:223], v154 offset:23552
	global_load_lds_dwordx4 v[4:5], off
	s_add_i32 m0, s74, 0x2000
	s_add_u32 s74, s40, 0xc0000
	v_lshl_add_u64 v[4:5], s[40:41], 0, v[136:137]
	s_addc_u32 s75, s41, 0
	s_add_i32 s76, s65, s54
	global_load_lds_dwordx4 v[4:5], off
	v_lshl_add_u64 v[4:5], s[74:75], 0, v[134:135]
	s_mov_b32 m0, s76
	s_nop 0
	global_load_lds_dwordx4 v[4:5], off
	v_lshl_add_u64 v[4:5], s[74:75], 0, v[136:137]
	s_add_i32 m0, s76, 0x2000
	s_nop 0
	global_load_lds_dwordx4 v[4:5], off
	v_lshl_add_u64 v[4:5], s[42:43], 0, v[134:135]
	s_mov_b32 m0, s55
	s_nop 0
	global_load_lds_dwordx4 v[4:5], off
	v_lshl_add_u64 v[4:5], s[42:43], 0, v[136:137]
	s_mov_b32 m0, s56
	s_nop 0
	global_load_lds_dwordx4 v[4:5], off
	s_waitcnt vmcnt(8)
	s_waitcnt lgkmcnt(0)
	s_barrier
; #define PG8_STAGE(bufoff, gbase, voff) do { _Pragma("unroll") for (int _i = 0; _i < 2; ++_i) \
;         __builtin_amdgcn_global_load_lds((const unsigned*)((const char*)(gbase) + (voff)[_i]), (PG8_LAS unsigned*)(lds + (bufoff) + ldsw + _i * 8192), 16, 0, 0); } while (0)
; #define PG8_LDA(dst, b, h) do { _Pragma("unroll") for (int m = 0; m < 4; ++m) _Pragma("unroll") for (int k = 0; k < 2; ++k) dst[m][k] = *(const PG8_LAS bf16x8*)(lds + PG8_SA(b, h) + aoff + m * 2048 + k * 1024); } while (0)
; #define PG8_LDB(dst, b, h) do { _Pragma("unroll") for (int n = 0; n < 2; ++n) _Pragma("unroll") for (int k = 0; k < 2; ++k) dst[n][k] = *(const PG8_LAS bf16x8*)(lds + PG8_SB(b, h) + boff + n * 2048 + k * 1024); } while (0)
; #define PG8_MMA(ai, bj, At, Bt) do { __builtin_amdgcn_s_setprio(1); _Pragma("unroll") for (int m = 0; m < 4; ++m) _Pragma("unroll") for (int n = 0; n < 2; ++n) _Pragma("unroll") for (int k = 0; k < 2; ++k) \
;         acc[ai][bj][m][n] = __builtin_amdgcn_mfma_f32_16x16x32_bf16(Bt[n][k], At[m][k], acc[ai][bj][m][n], 0, 0, 0); __builtin_amdgcn_s_setprio(0); } while (0)
; #define PG8_WAIT_V(n) asm volatile("s_waitcnt vmcnt(" #n ")" ::: "memory")
; #define PG8_WAIT_L(n) asm volatile("s_waitcnt lgkmcnt(" #n ")" ::: "memory")
; #define PG8_BAR __builtin_amdgcn_s_barrier()
; #define PG8_SCHED __builtin_amdgcn_sched_barrier(0)
; template <class Epi, class Sched, bool ALIGN_EPI = false, bool SP2 = false, bool RS = false, bool BPRE = false>
; __device__ __forceinline__ void gemm_phase(PG8_LAS unsigned char* lds, const Gemm g, const Sched& S, const Epi& E, const float* rs_ss = nullptr, PG8_LAS float* rs_tab = nullptr) {
;     ...
;             PG8_WAIT_V(8); PG8_WAIT_L(0); PG8_BAR; PG8_MMA(1, 0, At, B0); PG8_MMA(1, 1, At, B1); PG8_BAR; PG8_SCHED;
;             PG8_LDB(B0, 1, 0); PG8_LDB(B1, 1, 1); PG8_SCHED; PG8_LDA(At, 1, 0); PG8_STAGE(PG8_SA(0, 1), a2 + hstep, voffA);
;             PG8_WAIT_V(8); PG8_WAIT_L(0); PG8_BAR; PG8_MMA(0, 0, At, B0); PG8_MMA(0, 1, At, B1); PG8_BAR; PG8_SCHED;
	s_setprio 1
	s_waitcnt lgkmcnt(0)
	v_mfma_f32_16x16x32_bf16 v[66:69], v[160:163], v[192:195], 0
	v_mfma_f32_16x16x32_bf16 v[66:69], v[164:167], v[196:199], v[66:69]
	v_mfma_f32_16x16x32_bf16 v[62:65], v[172:175], v[196:199], 0
	v_mfma_f32_16x16x32_bf16 v[62:65], v[168:171], v[192:195], v[62:65]
	v_mfma_f32_16x16x32_bf16 v[46:49], v[168:171], v[200:203], 0
	v_mfma_f32_16x16x32_bf16 v[46:49], v[172:175], v[204:207], v[46:49]
	v_mfma_f32_16x16x32_bf16 v[50:53], v[164:167], v[204:207], 0
	v_mfma_f32_16x16x32_bf16 v[50:53], v[160:163], v[200:203], v[50:53]
	v_mfma_f32_16x16x32_bf16 v[34:37], v[160:163], v[208:211], 0
	v_mfma_f32_16x16x32_bf16 v[34:37], v[164:167], v[212:215], v[34:37]
	v_mfma_f32_16x16x32_bf16 v[30:33], v[172:175], v[212:215], 0
	v_mfma_f32_16x16x32_bf16 v[30:33], v[168:171], v[208:211], v[30:33]
	v_mfma_f32_16x16x32_bf16 v[14:17], v[168:171], v[216:219], 0
	v_mfma_f32_16x16x32_bf16 v[14:17], v[172:175], v[220:223], v[14:17]
	v_mfma_f32_16x16x32_bf16 v[18:21], v[164:167], v[220:223], 0
	v_mfma_f32_16x16x32_bf16 v[18:21], v[160:163], v[216:219], v[18:21]
	s_setprio 0
	s_setprio 1
	v_mfma_f32_16x16x32_bf16 v[10:13], v[176:179], v[216:219], 0
	v_mfma_f32_16x16x32_bf16 v[10:13], v[180:183], v[220:223], v[10:13]
	v_mfma_f32_16x16x32_bf16 v[4:7], v[188:191], v[220:223], 0
	v_mfma_f32_16x16x32_bf16 v[4:7], v[184:187], v[216:219], v[4:7]
	v_mfma_f32_16x16x32_bf16 v[22:25], v[184:187], v[208:211], 0
	v_mfma_f32_16x16x32_bf16 v[22:25], v[188:191], v[212:215], v[22:25]
	v_mfma_f32_16x16x32_bf16 v[26:29], v[180:183], v[212:215], 0
	v_mfma_f32_16x16x32_bf16 v[26:29], v[176:179], v[208:211], v[26:29]
	v_mfma_f32_16x16x32_bf16 v[42:45], v[176:179], v[200:203], 0
	v_mfma_f32_16x16x32_bf16 v[42:45], v[180:183], v[204:207], v[42:45]
	v_mfma_f32_16x16x32_bf16 v[38:41], v[188:191], v[204:207], 0
	v_mfma_f32_16x16x32_bf16 v[38:41], v[184:187], v[200:203], v[38:41]
	v_mfma_f32_16x16x32_bf16 v[54:57], v[184:187], v[192:195], 0
	v_mfma_f32_16x16x32_bf16 v[54:57], v[188:191], v[196:199], v[54:57]
	v_mfma_f32_16x16x32_bf16 v[58:61], v[180:183], v[196:199], 0
	v_mfma_f32_16x16x32_bf16 v[58:61], v[176:179], v[192:195], v[58:61]
	s_setprio 0
	s_barrier
	s_add_i32 s74, 0, 0x18000
	v_add_u32_e32 v3, s74, v150
	s_add_i32 s75, 0, 0x1c000
	ds_read_b128 v[160:163], v3
	ds_read_b128 v[164:167], v3 offset:1024
	ds_read_b128 v[168:171], v3 offset:2048
	ds_read_b128 v[172:175], v3 offset:3072
	v_add_u32_e32 v3, s75, v150
	ds_read_b128 v[176:179], v3
	ds_read_b128 v[180:183], v3 offset:1024
	ds_read_b128 v[184:187], v3 offset:2048
	ds_read_b128 v[188:191], v3 offset:3072
	s_add_u32 s42, s42, 0xc0000
	s_addc_u32 s43, s43, 0
	s_mov_b32 m0, s57
	v_lshl_add_u64 v[8:9], s[42:43], 0, v[134:135]
	ds_read_b128 v[192:195], v154 offset:32768
	ds_read_b128 v[196:199], v154 offset:33792
	ds_read_b128 v[200:203], v154 offset:34816
	ds_read_b128 v[204:207], v154 offset:35840
	ds_read_b128 v[208:211], v154 offset:36864
	ds_read_b128 v[212:215], v154 offset:37888
	ds_read_b128 v[216:219], v154 offset:38912
	ds_read_b128 v[220:223], v154 offset:39936
	global_load_lds_dwordx4 v[8:9], off
	v_lshl_add_u64 v[8:9], s[42:43], 0, v[136:137]
	s_mov_b32 m0, s58
	s_nop 0
	global_load_lds_dwordx4 v[8:9], off
	s_waitcnt vmcnt(8)
	s_waitcnt lgkmcnt(0)
	s_barrier
	s_setprio 1
	s_waitcnt lgkmcnt(0)
	v_mfma_f32_16x16x32_bf16 v[130:133], v[160:163], v[192:195], v[130:133]
	v_mfma_f32_16x16x32_bf16 v[130:133], v[164:167], v[196:199], v[130:133]
	v_mfma_f32_16x16x32_bf16 v[126:129], v[172:175], v[196:199], v[126:129]
	v_mfma_f32_16x16x32_bf16 v[126:129], v[168:171], v[192:195], v[126:129]
	v_mfma_f32_16x16x32_bf16 v[110:113], v[168:171], v[200:203], v[110:113]
	v_mfma_f32_16x16x32_bf16 v[110:113], v[172:175], v[204:207], v[110:113]
	v_mfma_f32_16x16x32_bf16 v[114:117], v[164:167], v[204:207], v[114:117]
	v_mfma_f32_16x16x32_bf16 v[114:117], v[160:163], v[200:203], v[114:117]
	v_mfma_f32_16x16x32_bf16 v[98:101], v[160:163], v[208:211], v[98:101]
	v_mfma_f32_16x16x32_bf16 v[98:101], v[164:167], v[212:215], v[98:101]
	v_mfma_f32_16x16x32_bf16 v[94:97], v[172:175], v[212:215], v[94:97]
	v_mfma_f32_16x16x32_bf16 v[94:97], v[168:171], v[208:211], v[94:97]
	v_mfma_f32_16x16x32_bf16 v[78:81], v[168:171], v[216:219], v[78:81]
	v_mfma_f32_16x16x32_bf16 v[78:81], v[172:175], v[220:223], v[78:81]
	v_mfma_f32_16x16x32_bf16 v[82:85], v[164:167], v[220:223], v[82:85]
	v_mfma_f32_16x16x32_bf16 v[82:85], v[160:163], v[216:219], v[82:85]
	s_setprio 0
	s_setprio 1
	v_mfma_f32_16x16x32_bf16 v[74:77], v[176:179], v[216:219], v[74:77]
	v_mfma_f32_16x16x32_bf16 v[74:77], v[180:183], v[220:223], v[74:77]
	v_mfma_f32_16x16x32_bf16 v[70:73], v[188:191], v[220:223], v[70:73]
	v_mfma_f32_16x16x32_bf16 v[70:73], v[184:187], v[216:219], v[70:73]
	v_mfma_f32_16x16x32_bf16 v[86:89], v[184:187], v[208:211], v[86:89]
	v_mfma_f32_16x16x32_bf16 v[86:89], v[188:191], v[212:215], v[86:89]
	v_mfma_f32_16x16x32_bf16 v[90:93], v[180:183], v[212:215], v[90:93]
	v_mfma_f32_16x16x32_bf16 v[90:93], v[176:179], v[208:211], v[90:93]
	v_mfma_f32_16x16x32_bf16 v[106:109], v[176:179], v[200:203], v[106:109]
	v_mfma_f32_16x16x32_bf16 v[106:109], v[180:183], v[204:207], v[106:109]
	v_mfma_f32_16x16x32_bf16 v[102:105], v[188:191], v[204:207], v[102:105]
	v_mfma_f32_16x16x32_bf16 v[102:105], v[184:187], v[200:203], v[102:105]
	v_mfma_f32_16x16x32_bf16 v[118:121], v[184:187], v[192:195], v[118:121]
	v_mfma_f32_16x16x32_bf16 v[118:121], v[188:191], v[196:199], v[118:121]
	v_mfma_f32_16x16x32_bf16 v[122:125], v[180:183], v[196:199], v[122:125]
	v_mfma_f32_16x16x32_bf16 v[122:125], v[176:179], v[192:195], v[122:125]
	s_setprio 0
	s_barrier
; #define PG8_STAGE(bufoff, gbase, voff) do { _Pragma("unroll") for (int _i = 0; _i < 2; ++_i) \
;         __builtin_amdgcn_global_load_lds((const unsigned*)((const char*)(gbase) + (voff)[_i]), (PG8_LAS unsigned*)(lds + (bufoff) + ldsw + _i * 8192), 16, 0, 0); } while (0)
; #define PG8_LDA(dst, b, h) do { _Pragma("unroll") for (int m = 0; m < 4; ++m) _Pragma("unroll") for (int k = 0; k < 2; ++k) dst[m][k] = *(const PG8_LAS bf16x8*)(lds + PG8_SA(b, h) + aoff + m * 2048 + k * 1024); } while (0)
; #define PG8_LDB(dst, b, h) do { _Pragma("unroll") for (int n = 0; n < 2; ++n) _Pragma("unroll") for (int k = 0; k < 2; ++k) dst[n][k] = *(const PG8_LAS bf16x8*)(lds + PG8_SB(b, h) + boff + n * 2048 + k * 1024); } while (0)
; #define PG8_MMA(ai, bj, At, Bt) do { __builtin_amdgcn_s_setprio(1); _Pragma("unroll") for (int m = 0; m < 4; ++m) _Pragma("unroll") for (int n = 0; n < 2; ++n) _Pragma("unroll") for (int k = 0; k < 2; ++k) \
;         acc[ai][bj][m][n] = __builtin_amdgcn_mfma_f32_16x16x32_bf16(Bt[n][k], At[m][k], acc[ai][bj][m][n], 0, 0, 0); __builtin_amdgcn_s_setprio(0); } while (0)
; #define PG8_WAIT_V(n) asm volatile("s_waitcnt vmcnt(" #n ")" ::: "memory")
; #define PG8_WAIT_L(n) asm volatile("s_waitcnt lgkmcnt(" #n ")" ::: "memory")
; #define PG8_BAR __builtin_amdgcn_s_barrier()
; #define PG8_SCHED __builtin_amdgcn_sched_barrier(0)
; template <class Epi, class Sched, bool ALIGN_EPI = false, bool SP2 = false, bool RS = false, bool BPRE = false>
; __device__ __forceinline__ void gemm_phase(PG8_LAS unsigned char* lds, const Gemm g, const Sched& S, const Epi& E, const float* rs_ss = nullptr, PG8_LAS float* rs_tab = nullptr) {
;     ...
;         for (int t = 0; t < nt; t += 2) {
;     ...
;             PG8_LDB(B0, 0, 0); PG8_LDB(B1, 0, 1); PG8_SCHED; PG8_LDA(At, 0, 0); PG8_STAGE(PG8_SA(1, 1), a1 + hstep, voffA);
;             PG8_WAIT_V(8); PG8_WAIT_L(0); PG8_BAR; PG8_MMA(0, 0, At, B0); PG8_MMA(0, 1, At, B1); PG8_BAR; PG8_SCHED;
;     ...
;             PG8_LDA(At, 1, 1); PG8_STAGE(PG8_SB(1, 0), b3, voffB); PG8_STAGE(PG8_SB(1, 1), b3 + hstep, voffB); PG8_STAGE(PG8_SA(1, 0), a3, voffA);
;             PG8_WAIT_V(8); PG8_WAIT_L(0); PG8_BAR; PG8_MMA(1, 0, At, B0); PG8_MMA(1, 1, At, B1); PG8_BAR; PG8_SCHED;
	s_add_u32 s42, s40, 0x4000
	s_addc_u32 s43, s41, 0
	s_add_i32 s74, s74, s54
	v_lshl_add_u64 v[8:9], s[42:43], 0, v[134:135]
	s_mov_b32 m0, s74
	ds_read_b128 v[192:195], v154 offset:49152
	ds_read_b128 v[196:199], v154 offset:50176
	ds_read_b128 v[200:203], v154 offset:51200
	ds_read_b128 v[204:207], v154 offset:52224
	ds_read_b128 v[208:211], v154 offset:53248
	ds_read_b128 v[212:215], v154 offset:54272
	ds_read_b128 v[216:219], v154 offset:55296
	ds_read_b128 v[220:223], v154 offset:56320
	global_load_lds_dwordx4 v[8:9], off
	s_add_i32 m0, s74, 0x2000
	s_add_u32 s40, s40, 0xc4000
	v_lshl_add_u64 v[8:9], s[42:43], 0, v[136:137]
	s_addc_u32 s41, s41, 0
	s_add_i32 s42, s75, s54
	global_load_lds_dwordx4 v[8:9], off
	v_lshl_add_u64 v[8:9], s[40:41], 0, v[134:135]
	s_mov_b32 m0, s42
	s_nop 0
	global_load_lds_dwordx4 v[8:9], off
	v_lshl_add_u64 v[8:9], s[40:41], 0, v[136:137]
	s_add_i32 m0, s42, 0x2000
	s_nop 0
	global_load_lds_dwordx4 v[8:9], off
	v_lshl_add_u64 v[8:9], s[38:39], 0, v[134:135]
	s_mov_b32 m0, s60
	s_nop 0
	global_load_lds_dwordx4 v[8:9], off
	v_lshl_add_u64 v[8:9], s[38:39], 0, v[136:137]
	s_mov_b32 m0, s61
	s_nop 0
	global_load_lds_dwordx4 v[8:9], off
	s_waitcnt vmcnt(8)
	s_waitcnt lgkmcnt(0)
	s_barrier
	s_setprio 1
	s_waitcnt lgkmcnt(0)
	v_mfma_f32_16x16x32_bf16 v[66:69], v[160:163], v[192:195], v[66:69]
	v_mfma_f32_16x16x32_bf16 v[66:69], v[164:167], v[196:199], v[66:69]
	v_mfma_f32_16x16x32_bf16 v[62:65], v[172:175], v[196:199], v[62:65]
	v_mfma_f32_16x16x32_bf16 v[62:65], v[168:171], v[192:195], v[62:65]
	v_mfma_f32_16x16x32_bf16 v[46:49], v[168:171], v[200:203], v[46:49]
	v_mfma_f32_16x16x32_bf16 v[46:49], v[172:175], v[204:207], v[46:49]
	v_mfma_f32_16x16x32_bf16 v[50:53], v[164:167], v[204:207], v[50:53]
	v_mfma_f32_16x16x32_bf16 v[50:53], v[160:163], v[200:203], v[50:53]
	v_mfma_f32_16x16x32_bf16 v[34:37], v[160:163], v[208:211], v[34:37]
	v_mfma_f32_16x16x32_bf16 v[34:37], v[164:167], v[212:215], v[34:37]
	v_mfma_f32_16x16x32_bf16 v[30:33], v[172:175], v[212:215], v[30:33]
	v_mfma_f32_16x16x32_bf16 v[30:33], v[168:171], v[208:211], v[30:33]
	v_mfma_f32_16x16x32_bf16 v[14:17], v[168:171], v[216:219], v[14:17]
	v_mfma_f32_16x16x32_bf16 v[14:17], v[172:175], v[220:223], v[14:17]
	v_mfma_f32_16x16x32_bf16 v[18:21], v[164:167], v[220:223], v[18:21]
	v_mfma_f32_16x16x32_bf16 v[18:21], v[160:163], v[216:219], v[18:21]
	s_setprio 0
	s_setprio 1
	v_mfma_f32_16x16x32_bf16 v[58:61], v[176:179], v[192:195], v[58:61]
	v_mfma_f32_16x16x32_bf16 v[58:61], v[180:183], v[196:199], v[58:61]
	v_mfma_f32_16x16x32_bf16 v[54:57], v[188:191], v[196:199], v[54:57]
	v_mfma_f32_16x16x32_bf16 v[54:57], v[184:187], v[192:195], v[54:57]
	v_mfma_f32_16x16x32_bf16 v[38:41], v[184:187], v[200:203], v[38:41]
	v_mfma_f32_16x16x32_bf16 v[38:41], v[188:191], v[204:207], v[38:41]
	v_mfma_f32_16x16x32_bf16 v[42:45], v[180:183], v[204:207], v[42:45]
	v_mfma_f32_16x16x32_bf16 v[42:45], v[176:179], v[200:203], v[42:45]
	v_mfma_f32_16x16x32_bf16 v[26:29], v[176:179], v[208:211], v[26:29]
	v_mfma_f32_16x16x32_bf16 v[26:29], v[180:183], v[212:215], v[26:29]
	v_mfma_f32_16x16x32_bf16 v[22:25], v[188:191], v[212:215], v[22:25]
	v_mfma_f32_16x16x32_bf16 v[22:25], v[184:187], v[208:211], v[22:25]
	v_mfma_f32_16x16x32_bf16 v[8:11], v[176:179], v[216:219], v[10:13]
	v_mfma_f32_16x16x32_bf16 v[10:13], v[180:183], v[220:223], v[8:11]
	v_mfma_f32_16x16x32_bf16 v[4:7], v[188:191], v[220:223], v[4:7]
	v_mfma_f32_16x16x32_bf16 v[6:9], v[184:187], v[216:219], v[4:7]
	s_setprio 0
	s_barrier
	s_add_i32 s38, s73, 2
	s_add_u32 s6, s6, 0x8000
	s_addc_u32 s7, s7, 0
	s_cmp_gt_u32 s73, 45
	s_mov_b32 s73, s38
	s_branch .LBB0_753
.LBB0_752:
	s_add_u32 s38, s10, s6
	v_add_u32_e32 v3, s64, v150
	s_addc_u32 s39, s11, s7
	ds_read_b128 v[160:163], v3
	ds_read_b128 v[164:167], v3 offset:1024
	ds_read_b128 v[168:171], v3 offset:2048
	ds_read_b128 v[172:175], v3 offset:3072
	v_add_u32_e32 v3, s65, v150
	s_add_u32 s38, s38, 0x8000
	ds_read_b128 v[176:179], v3
	ds_read_b128 v[180:183], v3 offset:1024
	ds_read_b128 v[184:187], v3 offset:2048
	ds_read_b128 v[188:191], v3 offset:3072
	s_addc_u32 s39, s39, 0
	s_add_u32 s40, s71, s6
	s_addc_u32 s41, s72, s7
	s_cmp_eq_u32 s6, 0xb8000
	s_cselect_b32 s42, s20, s38
	s_cselect_b32 s43, s21, s39
	s_cselect_b32 s40, s36, s40
	s_cselect_b32 s41, s37, s41
	s_add_u32 s38, s42, 0x4000
	s_addc_u32 s39, s43, 0
	v_lshl_add_u64 v[4:5], v[146:147], 0, s[6:7]
	s_add_i32 m0, s55, 0xc000
	ds_read_b128 v[192:195], v154
	ds_read_b128 v[196:199], v154 offset:1024
	ds_read_b128 v[200:203], v154 offset:2048
	ds_read_b128 v[204:207], v154 offset:3072
	ds_read_b128 v[208:211], v154 offset:4096
	ds_read_b128 v[212:215], v154 offset:5120
	ds_read_b128 v[216:219], v154 offset:6144
	ds_read_b128 v[220:223], v154 offset:7168
	global_load_lds_dwordx4 v[4:5], off
	v_lshl_add_u64 v[4:5], v[148:149], 0, s[6:7]
	s_add_i32 m0, s55, 0xe000
	s_nop 0
	global_load_lds_dwordx4 v[4:5], off
	s_waitcnt vmcnt(8)
	s_waitcnt lgkmcnt(0)
	s_barrier
; #define PG8_STAGE(bufoff, gbase, voff) do { _Pragma("unroll") for (int _i = 0; _i < 2; ++_i) \
;         __builtin_amdgcn_global_load_lds((const unsigned*)((const char*)(gbase) + (voff)[_i]), (PG8_LAS unsigned*)(lds + (bufoff) + ldsw + _i * 8192), 16, 0, 0); } while (0)
; #define PG8_LDA(dst, b, h) do { _Pragma("unroll") for (int m = 0; m < 4; ++m) _Pragma("unroll") for (int k = 0; k < 2; ++k) dst[m][k] = *(const PG8_LAS bf16x8*)(lds + PG8_SA(b, h) + aoff + m * 2048 + k * 1024); } while (0)
; #define PG8_LDB(dst, b, h) do { _Pragma("unroll") for (int n = 0; n < 2; ++n) _Pragma("unroll") for (int k = 0; k < 2; ++k) dst[n][k] = *(const PG8_LAS bf16x8*)(lds + PG8_SB(b, h) + boff + n * 2048 + k * 1024); } while (0)
; #define PG8_MMA(ai, bj, At, Bt) do { __builtin_amdgcn_s_setprio(1); _Pragma("unroll") for (int m = 0; m < 4; ++m) _Pragma("unroll") for (int n = 0; n < 2; ++n) _Pragma("unroll") for (int k = 0; k < 2; ++k) \
;         acc[ai][bj][m][n] = __builtin_amdgcn_mfma_f32_16x16x32_bf16(Bt[n][k], At[m][k], acc[ai][bj][m][n], 0, 0, 0); __builtin_amdgcn_s_setprio(0); } while (0)
; #define PG8_WAIT_V(n) asm volatile("s_waitcnt vmcnt(" #n ")" ::: "memory")
; #define PG8_WAIT_L(n) asm volatile("s_waitcnt lgkmcnt(" #n ")" ::: "memory")
; #define PG8_BAR __builtin_amdgcn_s_barrier()
; #define PG8_SCHED __builtin_amdgcn_sched_barrier(0)
; template <class Epi, class Sched, bool ALIGN_EPI = false, bool SP2 = false, bool RS = false, bool BPRE = false>
; __device__ __forceinline__ void gemm_phase(PG8_LAS unsigned char* lds, const Gemm g, const Sched& S, const Epi& E, const float* rs_ss = nullptr, PG8_LAS float* rs_tab = nullptr) {
;     ...
;             PG8_LDB(B0, 0, 0); PG8_LDB(B1, 0, 1); PG8_SCHED; PG8_LDA(At, 0, 0); PG8_STAGE(PG8_SA(1, 1), a1 + hstep, voffA);
;             PG8_WAIT_V(8); PG8_WAIT_L(0); PG8_BAR; PG8_MMA(0, 0, At, B0); PG8_MMA(0, 1, At, B1); PG8_BAR; PG8_SCHED;
;             PG8_LDA(At, 0, 1); PG8_STAGE(PG8_SB(0, 0), b2, voffB); PG8_STAGE(PG8_SB(0, 1), b2 + hstep, voffB); PG8_STAGE(PG8_SA(0, 0), a2, voffA);
;             PG8_WAIT_V(8); PG8_WAIT_L(0); PG8_BAR; PG8_MMA(1, 0, At, B0); PG8_MMA(1, 1, At, B1); PG8_BAR; PG8_SCHED;
	s_setprio 1
	s_waitcnt lgkmcnt(0)
	v_mfma_f32_16x16x32_bf16 v[130:133], v[160:163], v[192:195], v[130:133]
	v_mfma_f32_16x16x32_bf16 v[130:133], v[164:167], v[196:199], v[130:133]
	v_mfma_f32_16x16x32_bf16 v[126:129], v[172:175], v[196:199], v[126:129]
	v_mfma_f32_16x16x32_bf16 v[126:129], v[168:171], v[192:195], v[126:129]
	v_mfma_f32_16x16x32_bf16 v[110:113], v[168:171], v[200:203], v[110:113]
	v_mfma_f32_16x16x32_bf16 v[110:113], v[172:175], v[204:207], v[110:113]
	v_mfma_f32_16x16x32_bf16 v[114:117], v[164:167], v[204:207], v[114:117]
	v_mfma_f32_16x16x32_bf16 v[114:117], v[160:163], v[200:203], v[114:117]
	v_mfma_f32_16x16x32_bf16 v[98:101], v[160:163], v[208:211], v[98:101]
	v_mfma_f32_16x16x32_bf16 v[98:101], v[164:167], v[212:215], v[98:101]
	v_mfma_f32_16x16x32_bf16 v[94:97], v[172:175], v[212:215], v[94:97]
	v_mfma_f32_16x16x32_bf16 v[94:97], v[168:171], v[208:211], v[94:97]
	v_mfma_f32_16x16x32_bf16 v[78:81], v[168:171], v[216:219], v[78:81]
	v_mfma_f32_16x16x32_bf16 v[78:81], v[172:175], v[220:223], v[78:81]
	v_mfma_f32_16x16x32_bf16 v[82:85], v[164:167], v[220:223], v[82:85]
	v_mfma_f32_16x16x32_bf16 v[82:85], v[160:163], v[216:219], v[82:85]
	s_setprio 0
	s_setprio 1
	v_mfma_f32_16x16x32_bf16 v[74:77], v[176:179], v[216:219], v[74:77]
	v_mfma_f32_16x16x32_bf16 v[74:77], v[180:183], v[220:223], v[74:77]
	v_mfma_f32_16x16x32_bf16 v[70:73], v[188:191], v[220:223], v[70:73]
	v_mfma_f32_16x16x32_bf16 v[70:73], v[184:187], v[216:219], v[70:73]
	v_mfma_f32_16x16x32_bf16 v[86:89], v[184:187], v[208:211], v[86:89]
	v_mfma_f32_16x16x32_bf16 v[86:89], v[188:191], v[212:215], v[86:89]
	v_mfma_f32_16x16x32_bf16 v[90:93], v[180:183], v[212:215], v[90:93]
	v_mfma_f32_16x16x32_bf16 v[90:93], v[176:179], v[208:211], v[90:93]
	v_mfma_f32_16x16x32_bf16 v[106:109], v[176:179], v[200:203], v[106:109]
	v_mfma_f32_16x16x32_bf16 v[106:109], v[180:183], v[204:207], v[106:109]
	v_mfma_f32_16x16x32_bf16 v[102:105], v[188:191], v[204:207], v[102:105]
	v_mfma_f32_16x16x32_bf16 v[102:105], v[184:187], v[200:203], v[102:105]
	v_mfma_f32_16x16x32_bf16 v[118:121], v[184:187], v[192:195], v[118:121]
	v_mfma_f32_16x16x32_bf16 v[118:121], v[188:191], v[196:199], v[118:121]
	v_mfma_f32_16x16x32_bf16 v[122:125], v[180:183], v[196:199], v[122:125]
	v_mfma_f32_16x16x32_bf16 v[122:125], v[176:179], v[192:195], v[122:125]
	s_setprio 0
	s_barrier
	s_add_i32 s74, s64, s54
	v_lshl_add_u64 v[4:5], s[40:41], 0, v[134:135]
	s_mov_b32 m0, s74
	ds_read_b128 v[192:195], v154 offset:16384
	ds_read_b128 v[196:199], v154 offset:17408
	ds_read_b128 v[200:203], v154 offset:18432
	ds_read_b128 v[204:207], v154 offset:19456
	ds_read_b128 v[208:211], v154 offset:20480
	ds_read_b128 v[212:215], v154 offset:21504
	ds_read_b128 v[216:219], v154 offset:22528
	ds_read_b128 v[220:223], v154 offset:23552
	global_load_lds_dwordx4 v[4:5], off
	s_add_i32 m0, s74, 0x2000
	s_add_u32 s74, s40, 0xc0000
	v_lshl_add_u64 v[4:5], s[40:41], 0, v[136:137]
	s_addc_u32 s75, s41, 0
	s_add_i32 s76, s65, s54
	global_load_lds_dwordx4 v[4:5], off
	v_lshl_add_u64 v[4:5], s[74:75], 0, v[134:135]
	s_mov_b32 m0, s76
	s_nop 0
	global_load_lds_dwordx4 v[4:5], off
	v_lshl_add_u64 v[4:5], s[74:75], 0, v[136:137]
	s_add_i32 m0, s76, 0x2000
	s_nop 0
	global_load_lds_dwordx4 v[4:5], off
	v_lshl_add_u64 v[4:5], s[42:43], 0, v[134:135]
	s_mov_b32 m0, s55
	s_nop 0
	global_load_lds_dwordx4 v[4:5], off
	v_lshl_add_u64 v[4:5], s[42:43], 0, v[136:137]
	s_mov_b32 m0, s56
	s_nop 0
	global_load_lds_dwordx4 v[4:5], off
	s_waitcnt vmcnt(8)
	s_waitcnt lgkmcnt(0)
	s_barrier
	s_setprio 1
	s_waitcnt lgkmcnt(0)
	v_mfma_f32_16x16x32_bf16 v[66:69], v[160:163], v[192:195], v[66:69]
	v_mfma_f32_16x16x32_bf16 v[66:69], v[164:167], v[196:199], v[66:69]
	v_mfma_f32_16x16x32_bf16 v[62:65], v[172:175], v[196:199], v[62:65]
	v_mfma_f32_16x16x32_bf16 v[62:65], v[168:171], v[192:195], v[62:65]
	v_mfma_f32_16x16x32_bf16 v[46:49], v[168:171], v[200:203], v[46:49]
	v_mfma_f32_16x16x32_bf16 v[46:49], v[172:175], v[204:207], v[46:49]
	v_mfma_f32_16x16x32_bf16 v[50:53], v[164:167], v[204:207], v[50:53]
	v_mfma_f32_16x16x32_bf16 v[50:53], v[160:163], v[200:203], v[50:53]
	v_mfma_f32_16x16x32_bf16 v[34:37], v[160:163], v[208:211], v[34:37]
	v_mfma_f32_16x16x32_bf16 v[34:37], v[164:167], v[212:215], v[34:37]
	v_mfma_f32_16x16x32_bf16 v[30:33], v[172:175], v[212:215], v[30:33]
	v_mfma_f32_16x16x32_bf16 v[30:33], v[168:171], v[208:211], v[30:33]
	v_mfma_f32_16x16x32_bf16 v[14:17], v[168:171], v[216:219], v[14:17]
	v_mfma_f32_16x16x32_bf16 v[14:17], v[172:175], v[220:223], v[14:17]
	v_mfma_f32_16x16x32_bf16 v[18:21], v[164:167], v[220:223], v[18:21]
	v_mfma_f32_16x16x32_bf16 v[18:21], v[160:163], v[216:219], v[18:21]
	s_setprio 0
	s_setprio 1
	v_mfma_f32_16x16x32_bf16 v[10:13], v[176:179], v[216:219], v[10:13]
	v_mfma_f32_16x16x32_bf16 v[10:13], v[180:183], v[220:223], v[10:13]
	v_mfma_f32_16x16x32_bf16 v[4:7], v[188:191], v[220:223], v[6:9]
	v_mfma_f32_16x16x32_bf16 v[4:7], v[184:187], v[216:219], v[4:7]
	v_mfma_f32_16x16x32_bf16 v[22:25], v[184:187], v[208:211], v[22:25]
	v_mfma_f32_16x16x32_bf16 v[22:25], v[188:191], v[212:215], v[22:25]
	v_mfma_f32_16x16x32_bf16 v[26:29], v[180:183], v[212:215], v[26:29]
	v_mfma_f32_16x16x32_bf16 v[26:29], v[176:179], v[208:211], v[26:29]
	v_mfma_f32_16x16x32_bf16 v[42:45], v[176:179], v[200:203], v[42:45]
	v_mfma_f32_16x16x32_bf16 v[42:45], v[180:183], v[204:207], v[42:45]
	v_mfma_f32_16x16x32_bf16 v[38:41], v[188:191], v[204:207], v[38:41]
	v_mfma_f32_16x16x32_bf16 v[38:41], v[184:187], v[200:203], v[38:41]
	v_mfma_f32_16x16x32_bf16 v[54:57], v[184:187], v[192:195], v[54:57]
	v_mfma_f32_16x16x32_bf16 v[54:57], v[188:191], v[196:199], v[54:57]
	v_mfma_f32_16x16x32_bf16 v[58:61], v[180:183], v[196:199], v[58:61]
	v_mfma_f32_16x16x32_bf16 v[58:61], v[176:179], v[192:195], v[58:61]
	s_setprio 0
	s_barrier
; #define PG8_STAGE(bufoff, gbase, voff) do { _Pragma("unroll") for (int _i = 0; _i < 2; ++_i) \
;         __builtin_amdgcn_global_load_lds((const unsigned*)((const char*)(gbase) + (voff)[_i]), (PG8_LAS unsigned*)(lds + (bufoff) + ldsw + _i * 8192), 16, 0, 0); } while (0)
; #define PG8_LDA(dst, b, h) do { _Pragma("unroll") for (int m = 0; m < 4; ++m) _Pragma("unroll") for (int k = 0; k < 2; ++k) dst[m][k] = *(const PG8_LAS bf16x8*)(lds + PG8_SA(b, h) + aoff + m * 2048 + k * 1024); } while (0)
; #define PG8_LDB(dst, b, h) do { _Pragma("unroll") for (int n = 0; n < 2; ++n) _Pragma("unroll") for (int k = 0; k < 2; ++k) dst[n][k] = *(const PG8_LAS bf16x8*)(lds + PG8_SB(b, h) + boff + n * 2048 + k * 1024); } while (0)
; #define PG8_MMA(ai, bj, At, Bt) do { __builtin_amdgcn_s_setprio(1); _Pragma("unroll") for (int m = 0; m < 4; ++m) _Pragma("unroll") for (int n = 0; n < 2; ++n) _Pragma("unroll") for (int k = 0; k < 2; ++k) \
;         acc[ai][bj][m][n] = __builtin_amdgcn_mfma_f32_16x16x32_bf16(Bt[n][k], At[m][k], acc[ai][bj][m][n], 0, 0, 0); __builtin_amdgcn_s_setprio(0); } while (0)
; #define PG8_WAIT_V(n) asm volatile("s_waitcnt vmcnt(" #n ")" ::: "memory")
; #define PG8_WAIT_L(n) asm volatile("s_waitcnt lgkmcnt(" #n ")" ::: "memory")
; #define PG8_BAR __builtin_amdgcn_s_barrier()
; #define PG8_SCHED __builtin_amdgcn_sched_barrier(0)
; template <class Epi, class Sched, bool ALIGN_EPI = false, bool SP2 = false, bool RS = false, bool BPRE = false>
; __device__ __forceinline__ void gemm_phase(PG8_LAS unsigned char* lds, const Gemm g, const Sched& S, const Epi& E, const float* rs_ss = nullptr, PG8_LAS float* rs_tab = nullptr) {
;     ...
;             PG8_LDB(B0, 1, 0); PG8_LDB(B1, 1, 1); PG8_SCHED; PG8_LDA(At, 1, 0); PG8_STAGE(PG8_SA(0, 1), a2 + hstep, voffA);
;             PG8_WAIT_V(8); PG8_WAIT_L(0); PG8_BAR; PG8_MMA(0, 0, At, B0); PG8_MMA(0, 1, At, B1); PG8_BAR; PG8_SCHED;
	s_add_i32 s74, 0, 0x18000
	v_add_u32_e32 v3, s74, v150
	s_add_i32 s75, 0, 0x1c000
	ds_read_b128 v[160:163], v3
	ds_read_b128 v[164:167], v3 offset:1024
	ds_read_b128 v[168:171], v3 offset:2048
	ds_read_b128 v[172:175], v3 offset:3072
	v_add_u32_e32 v3, s75, v150
	ds_read_b128 v[176:179], v3
	ds_read_b128 v[180:183], v3 offset:1024
	ds_read_b128 v[184:187], v3 offset:2048
	ds_read_b128 v[188:191], v3 offset:3072
	s_add_u32 s42, s42, 0xc0000
	s_addc_u32 s43, s43, 0
	s_mov_b32 m0, s57
	v_lshl_add_u64 v[8:9], s[42:43], 0, v[134:135]
	ds_read_b128 v[192:195], v154 offset:32768
	ds_read_b128 v[196:199], v154 offset:33792
	ds_read_b128 v[200:203], v154 offset:34816
	ds_read_b128 v[204:207], v154 offset:35840
	ds_read_b128 v[208:211], v154 offset:36864
	ds_read_b128 v[212:215], v154 offset:37888
	ds_read_b128 v[216:219], v154 offset:38912
	ds_read_b128 v[220:223], v154 offset:39936
	global_load_lds_dwordx4 v[8:9], off
	v_lshl_add_u64 v[8:9], s[42:43], 0, v[136:137]
	s_mov_b32 m0, s58
	s_nop 0
	global_load_lds_dwordx4 v[8:9], off
	s_waitcnt vmcnt(8)
	s_waitcnt lgkmcnt(0)
	s_barrier
	s_setprio 1
	s_waitcnt lgkmcnt(0)
	v_mfma_f32_16x16x32_bf16 v[130:133], v[160:163], v[192:195], v[130:133]
	v_mfma_f32_16x16x32_bf16 v[130:133], v[164:167], v[196:199], v[130:133]
	v_mfma_f32_16x16x32_bf16 v[126:129], v[172:175], v[196:199], v[126:129]
	v_mfma_f32_16x16x32_bf16 v[126:129], v[168:171], v[192:195], v[126:129]
	v_mfma_f32_16x16x32_bf16 v[110:113], v[168:171], v[200:203], v[110:113]
	v_mfma_f32_16x16x32_bf16 v[110:113], v[172:175], v[204:207], v[110:113]
	v_mfma_f32_16x16x32_bf16 v[114:117], v[164:167], v[204:207], v[114:117]
	v_mfma_f32_16x16x32_bf16 v[114:117], v[160:163], v[200:203], v[114:117]
	v_mfma_f32_16x16x32_bf16 v[98:101], v[160:163], v[208:211], v[98:101]
	v_mfma_f32_16x16x32_bf16 v[98:101], v[164:167], v[212:215], v[98:101]
	v_mfma_f32_16x16x32_bf16 v[94:97], v[172:175], v[212:215], v[94:97]
	v_mfma_f32_16x16x32_bf16 v[94:97], v[168:171], v[208:211], v[94:97]
	v_mfma_f32_16x16x32_bf16 v[78:81], v[168:171], v[216:219], v[78:81]
	v_mfma_f32_16x16x32_bf16 v[78:81], v[172:175], v[220:223], v[78:81]
	v_mfma_f32_16x16x32_bf16 v[82:85], v[164:167], v[220:223], v[82:85]
	v_mfma_f32_16x16x32_bf16 v[82:85], v[160:163], v[216:219], v[82:85]
	s_setprio 0
	s_setprio 1
	v_mfma_f32_16x16x32_bf16 v[74:77], v[176:179], v[216:219], v[74:77]
	v_mfma_f32_16x16x32_bf16 v[74:77], v[180:183], v[220:223], v[74:77]
	v_mfma_f32_16x16x32_bf16 v[70:73], v[188:191], v[220:223], v[70:73]
	v_mfma_f32_16x16x32_bf16 v[70:73], v[184:187], v[216:219], v[70:73]
	v_mfma_f32_16x16x32_bf16 v[86:89], v[184:187], v[208:211], v[86:89]
	v_mfma_f32_16x16x32_bf16 v[86:89], v[188:191], v[212:215], v[86:89]
	v_mfma_f32_16x16x32_bf16 v[90:93], v[180:183], v[212:215], v[90:93]
	v_mfma_f32_16x16x32_bf16 v[90:93], v[176:179], v[208:211], v[90:93]
	v_mfma_f32_16x16x32_bf16 v[106:109], v[176:179], v[200:203], v[106:109]
	v_mfma_f32_16x16x32_bf16 v[106:109], v[180:183], v[204:207], v[106:109]
	v_mfma_f32_16x16x32_bf16 v[102:105], v[188:191], v[204:207], v[102:105]
	v_mfma_f32_16x16x32_bf16 v[102:105], v[184:187], v[200:203], v[102:105]
	v_mfma_f32_16x16x32_bf16 v[118:121], v[184:187], v[192:195], v[118:121]
	v_mfma_f32_16x16x32_bf16 v[118:121], v[188:191], v[196:199], v[118:121]
	v_mfma_f32_16x16x32_bf16 v[122:125], v[180:183], v[196:199], v[122:125]
	v_mfma_f32_16x16x32_bf16 v[122:125], v[176:179], v[192:195], v[122:125]
	s_setprio 0
	s_barrier
; #define PG8_STAGE(bufoff, gbase, voff) do { _Pragma("unroll") for (int _i = 0; _i < 2; ++_i) \
;         __builtin_amdgcn_global_load_lds((const unsigned*)((const char*)(gbase) + (voff)[_i]), (PG8_LAS unsigned*)(lds + (bufoff) + ldsw + _i * 8192), 16, 0, 0); } while (0)
; #define PG8_LDA(dst, b, h) do { _Pragma("unroll") for (int m = 0; m < 4; ++m) _Pragma("unroll") for (int k = 0; k < 2; ++k) dst[m][k] = *(const PG8_LAS bf16x8*)(lds + PG8_SA(b, h) + aoff + m * 2048 + k * 1024); } while (0)
; #define PG8_MMA(ai, bj, At, Bt) do { __builtin_amdgcn_s_setprio(1); _Pragma("unroll") for (int m = 0; m < 4; ++m) _Pragma("unroll") for (int n = 0; n < 2; ++n) _Pragma("unroll") for (int k = 0; k < 2; ++k) \
;         acc[ai][bj][m][n] = __builtin_amdgcn_mfma_f32_16x16x32_bf16(Bt[n][k], At[m][k], acc[ai][bj][m][n], 0, 0, 0); __builtin_amdgcn_s_setprio(0); } while (0)
; #define PG8_WAIT_V(n) asm volatile("s_waitcnt vmcnt(" #n ")" ::: "memory")
; #define PG8_WAIT_L(n) asm volatile("s_waitcnt lgkmcnt(" #n ")" ::: "memory")
; #define PG8_BAR __builtin_amdgcn_s_barrier()
; #define PG8_SCHED __builtin_amdgcn_sched_barrier(0)
; template <class Epi, class Sched, bool ALIGN_EPI = false, bool SP2 = false, bool RS = false, bool BPRE = false>
; __device__ __forceinline__ void gemm_phase(PG8_LAS unsigned char* lds, const Gemm g, const Sched& S, const Epi& E, const float* rs_ss = nullptr, PG8_LAS float* rs_tab = nullptr) {
;     ...
;         for (int t = 0; t < nt; t += 2) {
;     ...
;             PG8_LDA(At, 1, 1); PG8_STAGE(PG8_SB(1, 0), b3, voffB); PG8_STAGE(PG8_SB(1, 1), b3 + hstep, voffB); PG8_STAGE(PG8_SA(1, 0), a3, voffA);
;             PG8_WAIT_V(8); PG8_WAIT_L(0); PG8_BAR; PG8_MMA(1, 0, At, B0); PG8_MMA(1, 1, At, B1); PG8_BAR; PG8_SCHED;
	s_add_u32 s42, s40, 0x4000
	s_addc_u32 s43, s41, 0
	s_add_i32 s74, s74, s54
	v_lshl_add_u64 v[8:9], s[42:43], 0, v[134:135]
	s_mov_b32 m0, s74
	ds_read_b128 v[192:195], v154 offset:49152
	ds_read_b128 v[196:199], v154 offset:50176
	ds_read_b128 v[200:203], v154 offset:51200
	ds_read_b128 v[204:207], v154 offset:52224
	ds_read_b128 v[208:211], v154 offset:53248
	ds_read_b128 v[212:215], v154 offset:54272
	ds_read_b128 v[216:219], v154 offset:55296
	ds_read_b128 v[220:223], v154 offset:56320
	global_load_lds_dwordx4 v[8:9], off
	s_add_i32 m0, s74, 0x2000
	s_add_u32 s40, s40, 0xc4000
	v_lshl_add_u64 v[8:9], s[42:43], 0, v[136:137]
	s_addc_u32 s41, s41, 0
	s_add_i32 s42, s75, s54
	global_load_lds_dwordx4 v[8:9], off
	v_lshl_add_u64 v[8:9], s[40:41], 0, v[134:135]
	s_mov_b32 m0, s42
	s_nop 0
	global_load_lds_dwordx4 v[8:9], off
	v_lshl_add_u64 v[8:9], s[40:41], 0, v[136:137]
	s_add_i32 m0, s42, 0x2000
	s_nop 0
	global_load_lds_dwordx4 v[8:9], off
	v_lshl_add_u64 v[8:9], s[38:39], 0, v[134:135]
	s_mov_b32 m0, s60
	s_nop 0
	global_load_lds_dwordx4 v[8:9], off
	v_lshl_add_u64 v[8:9], s[38:39], 0, v[136:137]
	s_mov_b32 m0, s61
	s_nop 0
	global_load_lds_dwordx4 v[8:9], off
	s_waitcnt vmcnt(8)
	s_waitcnt lgkmcnt(0)
	s_barrier
	s_setprio 1
	s_waitcnt lgkmcnt(0)
	v_mfma_f32_16x16x32_bf16 v[66:69], v[160:163], v[192:195], v[66:69]
	v_mfma_f32_16x16x32_bf16 v[66:69], v[164:167], v[196:199], v[66:69]
	v_mfma_f32_16x16x32_bf16 v[62:65], v[172:175], v[196:199], v[62:65]
	v_mfma_f32_16x16x32_bf16 v[62:65], v[168:171], v[192:195], v[62:65]
	v_mfma_f32_16x16x32_bf16 v[46:49], v[168:171], v[200:203], v[46:49]
	v_mfma_f32_16x16x32_bf16 v[46:49], v[172:175], v[204:207], v[46:49]
	v_mfma_f32_16x16x32_bf16 v[50:53], v[164:167], v[204:207], v[50:53]
	v_mfma_f32_16x16x32_bf16 v[50:53], v[160:163], v[200:203], v[50:53]
	v_mfma_f32_16x16x32_bf16 v[34:37], v[160:163], v[208:211], v[34:37]
	v_mfma_f32_16x16x32_bf16 v[34:37], v[164:167], v[212:215], v[34:37]
	v_mfma_f32_16x16x32_bf16 v[30:33], v[172:175], v[212:215], v[30:33]
	v_mfma_f32_16x16x32_bf16 v[30:33], v[168:171], v[208:211], v[30:33]
	v_mfma_f32_16x16x32_bf16 v[14:17], v[168:171], v[216:219], v[14:17]
	v_mfma_f32_16x16x32_bf16 v[14:17], v[172:175], v[220:223], v[14:17]
	v_mfma_f32_16x16x32_bf16 v[18:21], v[164:167], v[220:223], v[18:21]
	v_mfma_f32_16x16x32_bf16 v[18:21], v[160:163], v[216:219], v[18:21]
	s_setprio 0
	s_setprio 1
	v_mfma_f32_16x16x32_bf16 v[58:61], v[176:179], v[192:195], v[58:61]
	v_mfma_f32_16x16x32_bf16 v[58:61], v[180:183], v[196:199], v[58:61]
	v_mfma_f32_16x16x32_bf16 v[54:57], v[188:191], v[196:199], v[54:57]
	v_mfma_f32_16x16x32_bf16 v[54:57], v[184:187], v[192:195], v[54:57]
	v_mfma_f32_16x16x32_bf16 v[38:41], v[184:187], v[200:203], v[38:41]
	v_mfma_f32_16x16x32_bf16 v[38:41], v[188:191], v[204:207], v[38:41]
	v_mfma_f32_16x16x32_bf16 v[42:45], v[180:183], v[204:207], v[42:45]
	v_mfma_f32_16x16x32_bf16 v[42:45], v[176:179], v[200:203], v[42:45]
	v_mfma_f32_16x16x32_bf16 v[26:29], v[176:179], v[208:211], v[26:29]
	v_mfma_f32_16x16x32_bf16 v[26:29], v[180:183], v[212:215], v[26:29]
	v_mfma_f32_16x16x32_bf16 v[22:25], v[188:191], v[212:215], v[22:25]
	v_mfma_f32_16x16x32_bf16 v[22:25], v[184:187], v[208:211], v[22:25]
	v_mfma_f32_16x16x32_bf16 v[8:11], v[176:179], v[216:219], v[10:13]
	v_mfma_f32_16x16x32_bf16 v[10:13], v[180:183], v[220:223], v[8:11]
	v_mfma_f32_16x16x32_bf16 v[4:7], v[188:191], v[220:223], v[4:7]
	v_mfma_f32_16x16x32_bf16 v[6:9], v[184:187], v[216:219], v[4:7]
	s_setprio 0
	s_barrier
	s_add_i32 s38, s73, 2
	s_add_u32 s6, s6, 0x8000
	s_addc_u32 s7, s7, 0
	s_cmp_gt_u32 s73, 45
	s_mov_b32 s73, s38
	s_cbranch_scc1 .LBB0_759
